# peeled first K-loop iteration of the four non-residual GEMM loops: first MFMA per accumulator takes inline 0 as SrcC, the 128 v_mov accumulator zeroings per unit are gone; rest as previous best
# speedup vs baseline: 1.0131x; 1.0131x over previous
; template <class Epi, class Sched, bool ALIGN_EPI = false, bool SP2 = false>
; __device__ __forceinline__ void gemm_phase(PG8_LAS unsigned char* lds, const Gemm g, const Sched& S, const Epi& E, const int wid) {
;     ...
;         const bool has_next = S.next(ui + 1, nxt);
;         const char* nA = !has_next ? cA : nxt.pn >= g.swap_pn ? (const char*)g.A2 + (size_t)(nxt.pn - g.swap_pn) * tstepA : (const char*)g.A + (size_t)nxt.pm * tstepA + (g.bd ? (size_t)(nxt.pn >> 1) * 512 : 0);
;         const char* nB = !has_next ? cB : nxt.pn >= g.swap_pn ? (const char*)g.B2 + (size_t)nxt.pm * tstepB : (const char*)g.Bt + (size_t)nxt.pn * tstepB;
;         for (int t = 0; t < nt; t += 2) {
;             const bool last = (t == nt - 2);
;             const char* a1 = cA + (size_t)(t + 1) * kstep;
;             const char* a2 = last ? nA : cA + (size_t)(t + 2) * kstep; const char* b2 = last ? nB : cB + (size_t)(t + 2) * kstep;
;             const char* a3 = a2 + kstep; const char* b3 = b2 + kstep;
;             if (last && has_next) S.a_ready(nxt);
;             if constexpr (SP2) {
;             PG8_LDB(B0, 0, 0); PG8_LDB(B1, 0, 1); PG8_SCHED; PG8_LDA(At, 0, 0); PG8_STAGE(PG8_SA(1, 1), a1 + hstepA, voffA);
;             PG8_WAIT_V(8); PG8_WAIT_L(0); PG8_BAR; PG8_MMA(0, 0, At, B0); PG8_MMA(0, 1, At, B1); PG8_BAR; PG8_SCHED;
;             PG8_LDA(At, 0, 1); PG8_STAGE(PG8_SB(0, 0), b2, voffB); PG8_STAGE(PG8_SB(0, 1), b2 + hstepB, voffB); PG8_STAGE(PG8_SA(0, 0), a2, voffA);
;             PG8_WAIT_V(8); PG8_WAIT_L(0); PG8_BAR; PG8_MMA(1, 0, At, B0); PG8_MMA(1, 1, At, B1); PG8_BAR; PG8_SCHED;
;             PG8_LDB(B0, 1, 0); PG8_LDB(B1, 1, 1); PG8_SCHED; PG8_LDA(At, 1, 0); PG8_STAGE(PG8_SA(0, 1), a2 + hstepA, voffA);
;             PG8_WAIT_V(8); PG8_WAIT_L(0); PG8_BAR; PG8_MMA(0, 0, At, B0); PG8_MMA(0, 1, At, B1); PG8_BAR; PG8_SCHED;
;             PG8_LDA(At, 1, 1); PG8_STAGE(PG8_SB(1, 0), b3, voffB); PG8_STAGE(PG8_SB(1, 1), b3 + hstepB, voffB); PG8_STAGE(PG8_SA(1, 0), a3, voffA);
;             PG8_WAIT_V(8); PG8_WAIT_L(0); PG8_BAR; PG8_MMA(1, 0, At, B0); PG8_MMA(1, 1, At, B1); PG8_BAR; PG8_SCHED;
;     ...
; #pragma unroll
;         for (int a = 0; a < 2; ++a)
; #pragma unroll
;             for (int b = 0; b < 2; ++b)
; #pragma unroll
;                 for (int m = 0; m < 4; ++m)
; #pragma unroll
;                     for (int n = 0; n < 2; ++n) acc[a][b][m][n] = (f32x4){0.f, 0.f, 0.f, 0.f};
.LBB0_117:
	s_ashr_i32 s35, s34, 31
	s_lshl_b64 s[36:37], s[34:35], 19
	s_add_u32 s7, s94, s36
	s_addc_u32 s31, s95, s37
	s_and_b64 s[36:37], s[4:5], exec
	s_cselect_b32 s37, s31, s45
	s_cselect_b32 s36, s7, s44
	s_ashr_i32 s31, s30, 31
	s_lshl_b64 s[38:39], s[30:31], 19
	s_add_u32 s7, s56, s38
	s_addc_u32 s31, s57, s39
	s_and_b64 s[38:39], s[4:5], exec
	s_cselect_b32 s39, s31, s47
	s_cselect_b32 s38, s7, s46
	s_andn2_b64 vcc, exec, s[18:19]
	s_cbranch_vccnz .LBB0_157
	s_add_u32 s44, s44, 0x40080
	s_addc_u32 s45, s45, 0
	s_add_u32 s7, s46, 0x100
	s_addc_u32 s31, s47, 0
	s_mov_b32 s35, 0
	ds_read_b128 v[144:147], v155
	ds_read_b128 v[148:151], v155 offset:1024
	ds_read_b128 v[158:161], v155 offset:2048
	ds_read_b128 v[162:165], v155 offset:3072
	ds_read_b128 v[166:169], v156
	ds_read_b128 v[170:173], v156 offset:1024
	ds_read_b128 v[174:177], v156 offset:2048
	ds_read_b128 v[180:183], v156 offset:3072
	s_add_i32 s41, s35, 2
	s_add_u32 s46, s44, 0xfffc0080
	s_addc_u32 s47, s45, -1
	s_cmp_eq_u32 s65, s35
	s_cselect_b32 s49, s37, s47
	s_cselect_b32 s48, s36, s46
	s_cselect_b32 s47, s39, s31
	s_cselect_b32 s46, s38, s7
	v_lshl_add_u64 v[216:217], s[44:45], 0, v[136:137]
	s_add_i32 m0, s58, 0xc000
	ds_read_b128 v[184:187], v157
	ds_read_b128 v[188:191], v157 offset:1024
	ds_read_b128 v[192:195], v157 offset:2048
	ds_read_b128 v[196:199], v157 offset:3072
	ds_read_b128 v[200:203], v157 offset:4096
	ds_read_b128 v[204:207], v157 offset:5120
	ds_read_b128 v[208:211], v157 offset:6144
	ds_read_b128 v[212:215], v157 offset:7168
	global_load_lds_dwordx4 v[216:217], off
	v_lshl_add_u64 v[216:217], s[44:45], 0, v[138:139]
	s_add_i32 m0, s58, 0xe000
	s_nop 0
	global_load_lds_dwordx4 v[216:217], off
	s_waitcnt vmcnt(8)
	s_waitcnt lgkmcnt(0)
	s_setprio 1
	s_barrier
	v_mfma_f32_16x16x32_bf16 v[124:127], v[144:147], v[184:187], 0
	v_mfma_f32_16x16x32_bf16 v[120:123], v[158:161], v[184:187], 0
	v_mfma_f32_16x16x32_bf16 v[108:111], v[144:147], v[192:195], 0
	v_mfma_f32_16x16x32_bf16 v[104:107], v[158:161], v[192:195], 0
	v_mfma_f32_16x16x32_bf16 v[92:95], v[144:147], v[200:203], 0
	v_mfma_f32_16x16x32_bf16 v[88:91], v[158:161], v[200:203], 0
	v_mfma_f32_16x16x32_bf16 v[76:79], v[144:147], v[208:211], 0
	v_mfma_f32_16x16x32_bf16 v[72:75], v[158:161], v[208:211], 0
	v_mfma_f32_16x16x32_bf16 v[124:127], v[148:151], v[188:191], v[124:127]
	v_mfma_f32_16x16x32_bf16 v[120:123], v[162:165], v[188:191], v[120:123]
	v_mfma_f32_16x16x32_bf16 v[108:111], v[148:151], v[196:199], v[108:111]
	v_mfma_f32_16x16x32_bf16 v[104:107], v[162:165], v[196:199], v[104:107]
	v_mfma_f32_16x16x32_bf16 v[92:95], v[148:151], v[204:207], v[92:95]
	v_mfma_f32_16x16x32_bf16 v[88:91], v[162:165], v[204:207], v[88:91]
	v_mfma_f32_16x16x32_bf16 v[76:79], v[148:151], v[212:215], v[76:79]
	v_mfma_f32_16x16x32_bf16 v[72:75], v[162:165], v[212:215], v[72:75]
	s_setprio 0
	s_setprio 1
	v_mfma_f32_16x16x32_bf16 v[116:119], v[166:169], v[184:187], 0
	v_mfma_f32_16x16x32_bf16 v[112:115], v[174:177], v[184:187], 0
	v_mfma_f32_16x16x32_bf16 v[100:103], v[166:169], v[192:195], 0
	v_mfma_f32_16x16x32_bf16 v[96:99], v[174:177], v[192:195], 0
	v_mfma_f32_16x16x32_bf16 v[84:87], v[166:169], v[200:203], 0
	v_mfma_f32_16x16x32_bf16 v[80:83], v[174:177], v[200:203], 0
	v_mfma_f32_16x16x32_bf16 v[68:71], v[166:169], v[208:211], 0
	v_mfma_f32_16x16x32_bf16 v[64:67], v[174:177], v[208:211], 0
	v_mfma_f32_16x16x32_bf16 v[116:119], v[170:173], v[188:191], v[116:119]
	v_mfma_f32_16x16x32_bf16 v[112:115], v[180:183], v[188:191], v[112:115]
	v_mfma_f32_16x16x32_bf16 v[100:103], v[170:173], v[196:199], v[100:103]
	v_mfma_f32_16x16x32_bf16 v[96:99], v[180:183], v[196:199], v[96:99]
	v_mfma_f32_16x16x32_bf16 v[84:87], v[170:173], v[204:207], v[84:87]
	v_mfma_f32_16x16x32_bf16 v[80:83], v[180:183], v[204:207], v[80:83]
	v_mfma_f32_16x16x32_bf16 v[68:71], v[170:173], v[212:215], v[68:71]
	v_mfma_f32_16x16x32_bf16 v[64:67], v[180:183], v[212:215], v[64:67]
	s_barrier
	s_setprio 0
	s_add_i32 s35, s69, s0
	v_lshl_add_u64 v[216:217], s[46:47], 0, v[130:131]
	s_mov_b32 m0, s35
	ds_read_b128 v[184:187], v157 offset:16384
	ds_read_b128 v[188:191], v157 offset:17408
	ds_read_b128 v[192:195], v157 offset:18432
	ds_read_b128 v[196:199], v157 offset:19456
	ds_read_b128 v[200:203], v157 offset:20480
	ds_read_b128 v[204:207], v157 offset:21504
	ds_read_b128 v[208:211], v157 offset:22528
	ds_read_b128 v[212:215], v157 offset:23552
	global_load_lds_dwordx4 v[216:217], off
	s_add_i32 m0, s35, 0x2000
	s_add_u32 s72, s46, 0x40000
	v_lshl_add_u64 v[218:219], s[46:47], 0, v[134:135]
	s_addc_u32 s73, s47, 0
	s_add_i32 s35, s70, s0
	global_load_lds_dwordx4 v[218:219], off
	v_lshl_add_u64 v[220:221], s[72:73], 0, v[130:131]
	s_mov_b32 m0, s35
	v_lshl_add_u64 v[222:223], s[48:49], 0, v[132:133]
	global_load_lds_dwordx4 v[220:221], off
	v_lshl_add_u64 v[220:221], s[72:73], 0, v[134:135]
	s_add_i32 m0, s35, 0x2000
	s_nop 0
	global_load_lds_dwordx4 v[220:221], off
	v_lshl_add_u64 v[220:221], s[48:49], 0, v[128:129]
	s_mov_b32 m0, s58
	s_nop 0
	global_load_lds_dwordx4 v[220:221], off
	s_mov_b32 m0, s59
	s_nop 0
	global_load_lds_dwordx4 v[222:223], off
	s_waitcnt vmcnt(8)
	s_waitcnt lgkmcnt(0)
	s_setprio 1
	s_barrier
; #define PG8_STAGE(bufoff, gbase, voff) do { _Pragma("unroll") for (int _i = 0; _i < 2; ++_i) \
;         __builtin_amdgcn_global_load_lds((const unsigned*)((const char*)(gbase) + (voff)[_i]), (PG8_LAS unsigned*)(lds + (bufoff) + ldsw + _i * 8192), 16, 0, 0); } while (0)
; #define PG8_LDA(dst, b, h) do { _Pragma("unroll") for (int m = 0; m < 4; ++m) _Pragma("unroll") for (int k = 0; k < 2; ++k) dst[m][k] = *(const PG8_LAS bf16x8*)(lds + PG8_SA(b, h) + aoff + m * 2048 + k * 1024); } while (0)
; #define PG8_LDB(dst, b, h) do { _Pragma("unroll") for (int n = 0; n < 2; ++n) _Pragma("unroll") for (int k = 0; k < 2; ++k) dst[n][k] = *(const PG8_LAS bf16x8*)(lds + PG8_SB(b, h) + boff + n * 2048 + k * 1024); } while (0)
; #define PG8_MMA(ai, bj, At, Bt) do { __builtin_amdgcn_s_setprio(1); _Pragma("unroll") for (int m = 0; m < 4; ++m) _Pragma("unroll") for (int n = 0; n < 2; ++n) _Pragma("unroll") for (int k = 0; k < 2; ++k) \
;         acc[ai][bj][m][n] = __builtin_amdgcn_mfma_f32_16x16x32_bf16(Bt[n][k], At[m][k], acc[ai][bj][m][n], 0, 0, 0); __builtin_amdgcn_s_setprio(0); } while (0)
; #define PG8_BAR __builtin_amdgcn_s_barrier()
; template <class Epi, class Sched, bool ALIGN_EPI = false, bool SP2 = false>
; __device__ __forceinline__ void gemm_phase(PG8_LAS unsigned char* lds, const Gemm g, const Sched& S, const Epi& E, const int wid) {
;     ...
;             PG8_LDB(B0, 0, 0); PG8_LDB(B1, 0, 1); PG8_SCHED; PG8_LDA(At, 0, 0); PG8_STAGE(PG8_SA(1, 1), a1 + hstepA, voffA);
;             PG8_WAIT_V(8); PG8_WAIT_L(0); PG8_BAR; PG8_MMA(0, 0, At, B0); PG8_MMA(0, 1, At, B1); PG8_BAR; PG8_SCHED;
;             PG8_LDA(At, 0, 1); PG8_STAGE(PG8_SB(0, 0), b2, voffB); PG8_STAGE(PG8_SB(0, 1), b2 + hstepB, voffB); PG8_STAGE(PG8_SA(0, 0), a2, voffA);
;             PG8_WAIT_V(8); PG8_WAIT_L(0); PG8_BAR; PG8_MMA(1, 0, At, B0); PG8_MMA(1, 1, At, B1); PG8_BAR; PG8_SCHED;
;             PG8_LDB(B0, 1, 0); PG8_LDB(B1, 1, 1); PG8_SCHED; PG8_LDA(At, 1, 0); PG8_STAGE(PG8_SA(0, 1), a2 + hstepA, voffA);
;             PG8_WAIT_V(8); PG8_WAIT_L(0); PG8_BAR; PG8_MMA(0, 0, At, B0); PG8_MMA(0, 1, At, B1); PG8_BAR; PG8_SCHED;
;             PG8_LDA(At, 1, 1); PG8_STAGE(PG8_SB(1, 0), b3, voffB); PG8_STAGE(PG8_SB(1, 1), b3 + hstepB, voffB); PG8_STAGE(PG8_SA(1, 0), a3, voffA);
;             PG8_WAIT_V(8); PG8_WAIT_L(0); PG8_BAR; PG8_MMA(1, 0, At, B0); PG8_MMA(1, 1, At, B1); PG8_BAR; PG8_SCHED;
	v_mfma_f32_16x16x32_bf16 v[60:63], v[144:147], v[184:187], 0
	v_mfma_f32_16x16x32_bf16 v[56:59], v[158:161], v[184:187], 0
	v_mfma_f32_16x16x32_bf16 v[44:47], v[144:147], v[192:195], 0
	v_mfma_f32_16x16x32_bf16 v[40:43], v[158:161], v[192:195], 0
	v_mfma_f32_16x16x32_bf16 v[28:31], v[144:147], v[200:203], 0
	v_mfma_f32_16x16x32_bf16 v[24:27], v[158:161], v[200:203], 0
	v_mfma_f32_16x16x32_bf16 v[12:15], v[144:147], v[208:211], 0
	v_mfma_f32_16x16x32_bf16 v[8:11], v[158:161], v[208:211], 0
	v_mfma_f32_16x16x32_bf16 v[60:63], v[148:151], v[188:191], v[60:63]
	v_mfma_f32_16x16x32_bf16 v[56:59], v[162:165], v[188:191], v[56:59]
	v_mfma_f32_16x16x32_bf16 v[44:47], v[148:151], v[196:199], v[44:47]
	v_mfma_f32_16x16x32_bf16 v[40:43], v[162:165], v[196:199], v[40:43]
	v_mfma_f32_16x16x32_bf16 v[28:31], v[148:151], v[204:207], v[28:31]
	v_mfma_f32_16x16x32_bf16 v[24:27], v[162:165], v[204:207], v[24:27]
	v_mfma_f32_16x16x32_bf16 v[12:15], v[148:151], v[212:215], v[12:15]
	v_mfma_f32_16x16x32_bf16 v[8:11], v[162:165], v[212:215], v[8:11]
	s_setprio 0
	s_setprio 1
	v_mfma_f32_16x16x32_bf16 v[52:55], v[166:169], v[184:187], 0
	v_mfma_f32_16x16x32_bf16 v[48:51], v[174:177], v[184:187], 0
	v_mfma_f32_16x16x32_bf16 v[36:39], v[166:169], v[192:195], 0
	v_mfma_f32_16x16x32_bf16 v[32:35], v[174:177], v[192:195], 0
	v_mfma_f32_16x16x32_bf16 v[20:23], v[166:169], v[200:203], 0
	v_mfma_f32_16x16x32_bf16 v[16:19], v[174:177], v[200:203], 0
	v_mfma_f32_16x16x32_bf16 v[4:7], v[166:169], v[208:211], 0
	v_mfma_f32_16x16x32_bf16 v[0:3], v[174:177], v[208:211], 0
	v_mfma_f32_16x16x32_bf16 v[52:55], v[170:173], v[188:191], v[52:55]
	v_mfma_f32_16x16x32_bf16 v[48:51], v[180:183], v[188:191], v[48:51]
	v_mfma_f32_16x16x32_bf16 v[36:39], v[170:173], v[196:199], v[36:39]
	v_mfma_f32_16x16x32_bf16 v[32:35], v[180:183], v[196:199], v[32:35]
	v_mfma_f32_16x16x32_bf16 v[20:23], v[170:173], v[204:207], v[20:23]
	v_mfma_f32_16x16x32_bf16 v[16:19], v[180:183], v[204:207], v[16:19]
	v_mfma_f32_16x16x32_bf16 v[4:7], v[170:173], v[212:215], v[4:7]
	v_mfma_f32_16x16x32_bf16 v[0:3], v[180:183], v[212:215], v[0:3]
	s_barrier
	s_setprio 0
	s_add_i32 s35, 0, 0x18000
	s_add_i32 s71, 0, 0x1c000
	v_add_u32_e32 v162, s35, v153
	v_add_u32_e32 v179, s71, v153
	ds_read_b128 v[144:147], v162
	ds_read_b128 v[148:151], v162 offset:1024
	ds_read_b128 v[158:161], v162 offset:2048
	ds_read_b128 v[162:165], v162 offset:3072
	ds_read_b128 v[166:169], v179
	ds_read_b128 v[170:173], v179 offset:1024
	ds_read_b128 v[174:177], v179 offset:2048
	ds_read_b128 v[180:183], v179 offset:3072
	s_add_u32 s48, s48, 0x40000
	s_addc_u32 s49, s49, 0
	s_mov_b32 m0, s60
	v_lshl_add_u64 v[224:225], s[48:49], 0, v[128:129]
	ds_read_b128 v[184:187], v157 offset:32768
	ds_read_b128 v[188:191], v157 offset:33792
	ds_read_b128 v[192:195], v157 offset:34816
	ds_read_b128 v[196:199], v157 offset:35840
	ds_read_b128 v[200:203], v157 offset:36864
	ds_read_b128 v[204:207], v157 offset:37888
	ds_read_b128 v[208:211], v157 offset:38912
	ds_read_b128 v[212:215], v157 offset:39936
	global_load_lds_dwordx4 v[224:225], off
	v_lshl_add_u64 v[224:225], s[48:49], 0, v[132:133]
	s_mov_b32 m0, s61
	s_nop 0
	global_load_lds_dwordx4 v[224:225], off
	s_waitcnt vmcnt(8)
	s_waitcnt lgkmcnt(0)
	s_setprio 1
	s_barrier
	v_mfma_f32_16x16x32_bf16 v[124:127], v[144:147], v[184:187], v[124:127]
	v_mfma_f32_16x16x32_bf16 v[120:123], v[158:161], v[184:187], v[120:123]
	v_mfma_f32_16x16x32_bf16 v[108:111], v[144:147], v[192:195], v[108:111]
	v_mfma_f32_16x16x32_bf16 v[104:107], v[158:161], v[192:195], v[104:107]
	v_mfma_f32_16x16x32_bf16 v[92:95], v[144:147], v[200:203], v[92:95]
	v_mfma_f32_16x16x32_bf16 v[88:91], v[158:161], v[200:203], v[88:91]
	v_mfma_f32_16x16x32_bf16 v[76:79], v[144:147], v[208:211], v[76:79]
	v_mfma_f32_16x16x32_bf16 v[72:75], v[158:161], v[208:211], v[72:75]
	v_mfma_f32_16x16x32_bf16 v[124:127], v[148:151], v[188:191], v[124:127]
	v_mfma_f32_16x16x32_bf16 v[120:123], v[162:165], v[188:191], v[120:123]
	v_mfma_f32_16x16x32_bf16 v[108:111], v[148:151], v[196:199], v[108:111]
	v_mfma_f32_16x16x32_bf16 v[104:107], v[162:165], v[196:199], v[104:107]
	v_mfma_f32_16x16x32_bf16 v[92:95], v[148:151], v[204:207], v[92:95]
	v_mfma_f32_16x16x32_bf16 v[88:91], v[162:165], v[204:207], v[88:91]
	v_mfma_f32_16x16x32_bf16 v[76:79], v[148:151], v[212:215], v[76:79]
	v_mfma_f32_16x16x32_bf16 v[72:75], v[162:165], v[212:215], v[72:75]
	s_setprio 0
	s_setprio 1
	v_mfma_f32_16x16x32_bf16 v[116:119], v[166:169], v[184:187], v[116:119]
	v_mfma_f32_16x16x32_bf16 v[112:115], v[174:177], v[184:187], v[112:115]
	v_mfma_f32_16x16x32_bf16 v[100:103], v[166:169], v[192:195], v[100:103]
	v_mfma_f32_16x16x32_bf16 v[96:99], v[174:177], v[192:195], v[96:99]
	v_mfma_f32_16x16x32_bf16 v[84:87], v[166:169], v[200:203], v[84:87]
	v_mfma_f32_16x16x32_bf16 v[80:83], v[174:177], v[200:203], v[80:83]
	v_mfma_f32_16x16x32_bf16 v[68:71], v[166:169], v[208:211], v[68:71]
	v_mfma_f32_16x16x32_bf16 v[64:67], v[174:177], v[208:211], v[64:67]
	v_mfma_f32_16x16x32_bf16 v[116:119], v[170:173], v[188:191], v[116:119]
	v_mfma_f32_16x16x32_bf16 v[112:115], v[180:183], v[188:191], v[112:115]
	v_mfma_f32_16x16x32_bf16 v[100:103], v[170:173], v[196:199], v[100:103]
	v_mfma_f32_16x16x32_bf16 v[96:99], v[180:183], v[196:199], v[96:99]
	v_mfma_f32_16x16x32_bf16 v[84:87], v[170:173], v[204:207], v[84:87]
	v_mfma_f32_16x16x32_bf16 v[80:83], v[180:183], v[204:207], v[80:83]
	v_mfma_f32_16x16x32_bf16 v[68:71], v[170:173], v[212:215], v[68:71]
	v_mfma_f32_16x16x32_bf16 v[64:67], v[180:183], v[212:215], v[64:67]
	s_barrier
; #define PG8_STAGE(bufoff, gbase, voff) do { _Pragma("unroll") for (int _i = 0; _i < 2; ++_i) \
;         __builtin_amdgcn_global_load_lds((const unsigned*)((const char*)(gbase) + (voff)[_i]), (PG8_LAS unsigned*)(lds + (bufoff) + ldsw + _i * 8192), 16, 0, 0); } while (0)
; #define PG8_LDA(dst, b, h) do { _Pragma("unroll") for (int m = 0; m < 4; ++m) _Pragma("unroll") for (int k = 0; k < 2; ++k) dst[m][k] = *(const PG8_LAS bf16x8*)(lds + PG8_SA(b, h) + aoff + m * 2048 + k * 1024); } while (0)
; #define PG8_MMA(ai, bj, At, Bt) do { __builtin_amdgcn_s_setprio(1); _Pragma("unroll") for (int m = 0; m < 4; ++m) _Pragma("unroll") for (int n = 0; n < 2; ++n) _Pragma("unroll") for (int k = 0; k < 2; ++k) \
;         acc[ai][bj][m][n] = __builtin_amdgcn_mfma_f32_16x16x32_bf16(Bt[n][k], At[m][k], acc[ai][bj][m][n], 0, 0, 0); __builtin_amdgcn_s_setprio(0); } while (0)
; #define PG8_WAIT_V(n) asm volatile("s_waitcnt vmcnt(" #n ")" ::: "memory")
; #define PG8_WAIT_L(n) asm volatile("s_waitcnt lgkmcnt(" #n ")" ::: "memory")
; #define PG8_BAR __builtin_amdgcn_s_barrier()
; #define PG8_SCHED __builtin_amdgcn_sched_barrier(0)
; template <class Epi, class Sched, bool ALIGN_EPI = false, bool SP2 = false>
; __device__ __forceinline__ void gemm_phase(PG8_LAS unsigned char* lds, const Gemm g, const Sched& S, const Epi& E, const int wid) {
;     ...
;         for (int t = 0; t < nt; t += 2) {
;             const bool last = (t == nt - 2);
;             const char* a1 = cA + (size_t)(t + 1) * kstep;
;             const char* a2 = last ? nA : cA + (size_t)(t + 2) * kstep; const char* b2 = last ? nB : cB + (size_t)(t + 2) * kstep;
;             const char* a3 = a2 + kstep; const char* b3 = b2 + kstep;
;     ...
;             PG8_LDA(At, 1, 1); PG8_STAGE(PG8_SB(1, 0), b3, voffB); PG8_STAGE(PG8_SB(1, 1), b3 + hstepB, voffB); PG8_STAGE(PG8_SA(1, 0), a3, voffA);
;             PG8_WAIT_V(8); PG8_WAIT_L(0); PG8_BAR; PG8_MMA(1, 0, At, B0); PG8_MMA(1, 1, At, B1); PG8_BAR; PG8_SCHED;
	s_setprio 0
	s_add_i32 s35, s35, s0
	v_lshl_add_u64 v[216:217], v[216:217], 0, s[12:13]
	s_mov_b32 m0, s35
	ds_read_b128 v[184:187], v157 offset:49152
	ds_read_b128 v[188:191], v157 offset:50176
	ds_read_b128 v[192:195], v157 offset:51200
	ds_read_b128 v[196:199], v157 offset:52224
	ds_read_b128 v[200:203], v157 offset:53248
	ds_read_b128 v[204:207], v157 offset:54272
	ds_read_b128 v[208:211], v157 offset:55296
	ds_read_b128 v[212:215], v157 offset:56320
	global_load_lds_dwordx4 v[216:217], off
	s_add_i32 m0, s35, 0x2000
	s_add_u32 s46, s46, 0x40080
	v_lshl_add_u64 v[216:217], v[218:219], 0, s[12:13]
	s_addc_u32 s47, s47, 0
	s_add_i32 s35, s71, s0
	global_load_lds_dwordx4 v[216:217], off
	v_lshl_add_u64 v[216:217], s[46:47], 0, v[130:131]
	s_mov_b32 m0, s35
	s_nop 0
	global_load_lds_dwordx4 v[216:217], off
	v_lshl_add_u64 v[216:217], s[46:47], 0, v[134:135]
	s_add_i32 m0, s35, 0x2000
	s_nop 0
	global_load_lds_dwordx4 v[216:217], off
	v_lshl_add_u64 v[216:217], v[220:221], 0, s[12:13]
	s_mov_b32 m0, s63
	s_nop 0
	global_load_lds_dwordx4 v[216:217], off
	v_lshl_add_u64 v[216:217], v[222:223], 0, s[12:13]
	s_mov_b32 m0, s64
	s_nop 0
	global_load_lds_dwordx4 v[216:217], off
	s_waitcnt vmcnt(8)
	s_waitcnt lgkmcnt(0)
	s_setprio 1
	s_barrier
	v_mfma_f32_16x16x32_bf16 v[60:63], v[144:147], v[184:187], v[60:63]
	v_mfma_f32_16x16x32_bf16 v[56:59], v[158:161], v[184:187], v[56:59]
	v_mfma_f32_16x16x32_bf16 v[44:47], v[144:147], v[192:195], v[44:47]
	v_mfma_f32_16x16x32_bf16 v[40:43], v[158:161], v[192:195], v[40:43]
	v_mfma_f32_16x16x32_bf16 v[28:31], v[144:147], v[200:203], v[28:31]
	v_mfma_f32_16x16x32_bf16 v[24:27], v[158:161], v[200:203], v[24:27]
	v_mfma_f32_16x16x32_bf16 v[12:15], v[144:147], v[208:211], v[12:15]
	v_mfma_f32_16x16x32_bf16 v[8:11], v[158:161], v[208:211], v[8:11]
	v_mfma_f32_16x16x32_bf16 v[60:63], v[148:151], v[188:191], v[60:63]
	v_mfma_f32_16x16x32_bf16 v[56:59], v[162:165], v[188:191], v[56:59]
	v_mfma_f32_16x16x32_bf16 v[44:47], v[148:151], v[196:199], v[44:47]
	v_mfma_f32_16x16x32_bf16 v[40:43], v[162:165], v[196:199], v[40:43]
	v_mfma_f32_16x16x32_bf16 v[28:31], v[148:151], v[204:207], v[28:31]
	v_mfma_f32_16x16x32_bf16 v[24:27], v[162:165], v[204:207], v[24:27]
	v_mfma_f32_16x16x32_bf16 v[12:15], v[148:151], v[212:215], v[12:15]
	v_mfma_f32_16x16x32_bf16 v[8:11], v[162:165], v[212:215], v[8:11]
	s_setprio 0
	s_setprio 1
	v_mfma_f32_16x16x32_bf16 v[52:55], v[166:169], v[184:187], v[52:55]
	v_mfma_f32_16x16x32_bf16 v[48:51], v[174:177], v[184:187], v[48:51]
	v_mfma_f32_16x16x32_bf16 v[36:39], v[166:169], v[192:195], v[36:39]
	v_mfma_f32_16x16x32_bf16 v[32:35], v[174:177], v[192:195], v[32:35]
	v_mfma_f32_16x16x32_bf16 v[20:23], v[166:169], v[200:203], v[20:23]
	v_mfma_f32_16x16x32_bf16 v[16:19], v[174:177], v[200:203], v[16:19]
	v_mfma_f32_16x16x32_bf16 v[4:7], v[166:169], v[208:211], v[4:7]
	v_mfma_f32_16x16x32_bf16 v[0:3], v[174:177], v[208:211], v[0:3]
	v_mfma_f32_16x16x32_bf16 v[52:55], v[170:173], v[188:191], v[52:55]
	v_mfma_f32_16x16x32_bf16 v[48:51], v[180:183], v[188:191], v[48:51]
	v_mfma_f32_16x16x32_bf16 v[36:39], v[170:173], v[196:199], v[36:39]
	v_mfma_f32_16x16x32_bf16 v[32:35], v[180:183], v[196:199], v[32:35]
	v_mfma_f32_16x16x32_bf16 v[20:23], v[170:173], v[204:207], v[20:23]
	v_mfma_f32_16x16x32_bf16 v[16:19], v[180:183], v[204:207], v[16:19]
	v_mfma_f32_16x16x32_bf16 v[4:7], v[170:173], v[212:215], v[4:7]
	v_mfma_f32_16x16x32_bf16 v[0:3], v[180:183], v[212:215], v[0:3]
	s_barrier
	s_setprio 0
	s_add_u32 s44, s44, 0x100
	s_addc_u32 s45, s45, 0
	s_add_u32 s7, s7, 0x100
	s_addc_u32 s31, s31, 0
	s_cmp_ge_i32 s41, s55
	s_mov_b32 s35, s41
	s_cbranch_scc0 .LBB0_119
	s_branch .Lpeel_after_119

; #define PG8_BAR __builtin_amdgcn_s_barrier()
; template <class Epi, class Sched, bool ALIGN_EPI = false, bool SP2 = false>
; __device__ __forceinline__ void gemm_phase(PG8_LAS unsigned char* lds, const Gemm g, const Sched& S, const Epi& E, const int wid) {
;     ...
;         if constexpr (ALIGN_EPI) { if (wr == 0) PG8_BAR; }
;         if constexpr (!Epi::AFTER_DRAIN) { E(acc, cur, wr, wc, fr, fq); S.done(cur); }
.Lpeel_after_119:
	v_readlane_b32 s72, v250, 29
	s_and_b64 vcc, exec, s[24:25]
	s_cbranch_vccz .LBB0_122

; template <class Epi, class Sched, bool ALIGN_EPI = false, bool SP2 = false>
; __device__ __forceinline__ void gemm_phase(PG8_LAS unsigned char* lds, const Gemm g, const Sched& S, const Epi& E, const int wid) {
;     ...
;         const bool has_next = S.next(ui + 1, nxt);
;         const char* nA = !has_next ? cA : nxt.pn >= g.swap_pn ? (const char*)g.A2 + (size_t)(nxt.pn - g.swap_pn) * tstepA : (const char*)g.A + (size_t)nxt.pm * tstepA + (g.bd ? (size_t)(nxt.pn >> 1) * 512 : 0);
;         const char* nB = !has_next ? cB : nxt.pn >= g.swap_pn ? (const char*)g.B2 + (size_t)nxt.pm * tstepB : (const char*)g.Bt + (size_t)nxt.pn * tstepB;
;         for (int t = 0; t < nt; t += 2) {
;             const bool last = (t == nt - 2);
;             const char* a1 = cA + (size_t)(t + 1) * kstep;
;             const char* a2 = last ? nA : cA + (size_t)(t + 2) * kstep; const char* b2 = last ? nB : cB + (size_t)(t + 2) * kstep;
;             const char* a3 = a2 + kstep; const char* b3 = b2 + kstep;
;             if (last && has_next) S.a_ready(nxt);
;             if constexpr (SP2) {
;             PG8_LDB(B0, 0, 0); PG8_LDB(B1, 0, 1); PG8_SCHED; PG8_LDA(At, 0, 0); PG8_STAGE(PG8_SA(1, 1), a1 + hstepA, voffA);
;             PG8_WAIT_V(8); PG8_WAIT_L(0); PG8_BAR; PG8_MMA(0, 0, At, B0); PG8_MMA(0, 1, At, B1); PG8_BAR; PG8_SCHED;
;             PG8_LDA(At, 0, 1); PG8_STAGE(PG8_SB(0, 0), b2, voffB); PG8_STAGE(PG8_SB(0, 1), b2 + hstepB, voffB); PG8_STAGE(PG8_SA(0, 0), a2, voffA);
;             PG8_WAIT_V(8); PG8_WAIT_L(0); PG8_BAR; PG8_MMA(1, 0, At, B0); PG8_MMA(1, 1, At, B1); PG8_BAR; PG8_SCHED;
;             PG8_LDB(B0, 1, 0); PG8_LDB(B1, 1, 1); PG8_SCHED; PG8_LDA(At, 1, 0); PG8_STAGE(PG8_SA(0, 1), a2 + hstepA, voffA);
;             PG8_WAIT_V(8); PG8_WAIT_L(0); PG8_BAR; PG8_MMA(0, 0, At, B0); PG8_MMA(0, 1, At, B1); PG8_BAR; PG8_SCHED;
;             PG8_LDA(At, 1, 1); PG8_STAGE(PG8_SB(1, 0), b3, voffB); PG8_STAGE(PG8_SB(1, 1), b3 + hstepB, voffB); PG8_STAGE(PG8_SA(1, 0), a3, voffA);
;             PG8_WAIT_V(8); PG8_WAIT_L(0); PG8_BAR; PG8_MMA(1, 0, At, B0); PG8_MMA(1, 1, At, B1); PG8_BAR; PG8_SCHED;
;     ...
; #pragma unroll
;         for (int a = 0; a < 2; ++a)
; #pragma unroll
;             for (int b = 0; b < 2; ++b)
; #pragma unroll
;                 for (int m = 0; m < 4; ++m)
; #pragma unroll
;                     for (int n = 0; n < 2; ++n) acc[a][b][m][n] = (f32x4){0.f, 0.f, 0.f, 0.f};
.LBB0_268:
	s_ashr_i32 s35, s34, 31
	s_lshl_b64 s[48:49], s[34:35], 17
	s_add_u32 s35, s55, s48
	s_addc_u32 s37, s56, s49
	s_and_b64 s[6:7], s[6:7], exec
	s_cselect_b32 s7, s37, s47
	s_cselect_b32 s6, s35, s46
	s_andn2_b64 vcc, exec, s[24:25]
	s_cbranch_vccnz .LBB0_276
	s_add_u32 s44, s44, 0x40080
	s_addc_u32 s45, s45, 0
	s_add_u32 s35, s46, 0x100
	s_addc_u32 s37, s47, 0
	s_mov_b32 s46, 0
	ds_read_b128 v[60:63], v182
	ds_read_b128 v[68:71], v182 offset:1024
	ds_read_b128 v[72:75], v182 offset:2048
	ds_read_b128 v[76:79], v182 offset:3072
	ds_read_b128 v[80:83], v183
	ds_read_b128 v[84:87], v183 offset:1024
	ds_read_b128 v[172:175], v183 offset:2048
	ds_read_b128 v[186:189], v183 offset:3072
	s_add_i32 s68, s46, 2
	s_add_u32 s47, s44, 0xfffc0080
	s_addc_u32 s48, s45, -1
	s_cmp_eq_u32 s63, s46
	s_cselect_b32 s46, s6, s35
	s_cselect_b32 s49, s39, s48
	s_cselect_b32 s48, s38, s47
	s_cselect_b32 s47, s7, s37
	v_lshl_add_u64 v[176:177], s[44:45], 0, v[162:163]
	s_add_i32 m0, s41, 0xc000
	ds_read_b128 v[190:193], v184
	ds_read_b128 v[194:197], v184 offset:1024
	ds_read_b128 v[198:201], v184 offset:2048
	ds_read_b128 v[202:205], v184 offset:3072
	ds_read_b128 v[206:209], v184 offset:4096
	ds_read_b128 v[210:213], v184 offset:5120
	ds_read_b128 v[214:217], v184 offset:6144
	ds_read_b128 v[218:221], v184 offset:7168
	global_load_lds_dwordx4 v[176:177], off
	v_lshl_add_u64 v[176:177], s[44:45], 0, v[164:165]
	s_add_i32 m0, s41, 0xe000
	s_nop 0
	global_load_lds_dwordx4 v[176:177], off
	s_waitcnt vmcnt(8)
	s_waitcnt lgkmcnt(0)
	s_setprio 1
	s_barrier
	v_mfma_f32_16x16x32_bf16 v[148:151], v[60:63], v[190:193], 0
	v_mfma_f32_16x16x32_bf16 v[140:143], v[72:75], v[190:193], 0
	v_mfma_f32_16x16x32_bf16 v[132:135], v[60:63], v[198:201], 0
	v_mfma_f32_16x16x32_bf16 v[124:127], v[72:75], v[198:201], 0
	v_mfma_f32_16x16x32_bf16 v[116:119], v[60:63], v[206:209], 0
	v_mfma_f32_16x16x32_bf16 v[108:111], v[72:75], v[206:209], 0
	v_mfma_f32_16x16x32_bf16 v[100:103], v[60:63], v[214:217], 0
	v_mfma_f32_16x16x32_bf16 v[92:95], v[72:75], v[214:217], 0
	v_mfma_f32_16x16x32_bf16 v[148:151], v[68:71], v[194:197], v[148:151]
	v_mfma_f32_16x16x32_bf16 v[140:143], v[76:79], v[194:197], v[140:143]
	v_mfma_f32_16x16x32_bf16 v[132:135], v[68:71], v[202:205], v[132:135]
	v_mfma_f32_16x16x32_bf16 v[124:127], v[76:79], v[202:205], v[124:127]
	v_mfma_f32_16x16x32_bf16 v[116:119], v[68:71], v[210:213], v[116:119]
	v_mfma_f32_16x16x32_bf16 v[108:111], v[76:79], v[210:213], v[108:111]
	v_mfma_f32_16x16x32_bf16 v[100:103], v[68:71], v[218:221], v[100:103]
	v_mfma_f32_16x16x32_bf16 v[92:95], v[76:79], v[218:221], v[92:95]
	s_setprio 0
	s_setprio 1
	v_mfma_f32_16x16x32_bf16 v[144:147], v[80:83], v[190:193], 0
	v_mfma_f32_16x16x32_bf16 v[136:139], v[172:175], v[190:193], 0
	v_mfma_f32_16x16x32_bf16 v[128:131], v[80:83], v[198:201], 0
	v_mfma_f32_16x16x32_bf16 v[120:123], v[172:175], v[198:201], 0
	v_mfma_f32_16x16x32_bf16 v[112:115], v[80:83], v[206:209], 0
	v_mfma_f32_16x16x32_bf16 v[104:107], v[172:175], v[206:209], 0
	v_mfma_f32_16x16x32_bf16 v[96:99], v[80:83], v[214:217], 0
	v_mfma_f32_16x16x32_bf16 v[88:91], v[172:175], v[214:217], 0
	v_mfma_f32_16x16x32_bf16 v[144:147], v[84:87], v[194:197], v[144:147]
	v_mfma_f32_16x16x32_bf16 v[136:139], v[186:189], v[194:197], v[136:139]
	v_mfma_f32_16x16x32_bf16 v[128:131], v[84:87], v[202:205], v[128:131]
	v_mfma_f32_16x16x32_bf16 v[120:123], v[186:189], v[202:205], v[120:123]
	v_mfma_f32_16x16x32_bf16 v[112:115], v[84:87], v[210:213], v[112:115]
	v_mfma_f32_16x16x32_bf16 v[104:107], v[186:189], v[210:213], v[104:107]
	v_mfma_f32_16x16x32_bf16 v[96:99], v[84:87], v[218:221], v[96:99]
	v_mfma_f32_16x16x32_bf16 v[88:91], v[186:189], v[218:221], v[88:91]
	s_barrier
	s_setprio 0
	s_add_i32 s69, s64, s0
	v_lshl_add_u64 v[176:177], s[46:47], 0, v[154:155]
	s_mov_b32 m0, s69
	ds_read_b128 v[190:193], v184 offset:16384
	ds_read_b128 v[194:197], v184 offset:17408
	ds_read_b128 v[198:201], v184 offset:18432
	ds_read_b128 v[202:205], v184 offset:19456
	ds_read_b128 v[206:209], v184 offset:20480
	ds_read_b128 v[210:213], v184 offset:21504
	ds_read_b128 v[214:217], v184 offset:22528
	ds_read_b128 v[218:221], v184 offset:23552
	global_load_lds_dwordx4 v[176:177], off
	s_add_i32 m0, s69, 0x2000
	s_add_u32 s70, s46, 0x10000
	v_lshl_add_u64 v[222:223], s[46:47], 0, v[158:159]
	s_addc_u32 s71, s47, 0
	s_add_i32 s69, s65, s0
	global_load_lds_dwordx4 v[222:223], off
	v_lshl_add_u64 v[224:225], s[70:71], 0, v[154:155]
	s_mov_b32 m0, s69
	v_lshl_add_u64 v[226:227], s[48:49], 0, v[156:157]
	global_load_lds_dwordx4 v[224:225], off
	v_lshl_add_u64 v[224:225], s[70:71], 0, v[158:159]
	s_add_i32 m0, s69, 0x2000
	s_nop 0
	global_load_lds_dwordx4 v[224:225], off
	v_lshl_add_u64 v[224:225], s[48:49], 0, v[152:153]
	s_mov_b32 m0, s41
	s_nop 0
	global_load_lds_dwordx4 v[224:225], off
	s_mov_b32 m0, s57
	s_nop 0
	global_load_lds_dwordx4 v[226:227], off
	s_waitcnt vmcnt(8)
	s_waitcnt lgkmcnt(0)
	s_setprio 1
	s_barrier
; #define PG8_STAGE(bufoff, gbase, voff) do { _Pragma("unroll") for (int _i = 0; _i < 2; ++_i) \
;         __builtin_amdgcn_global_load_lds((const unsigned*)((const char*)(gbase) + (voff)[_i]), (PG8_LAS unsigned*)(lds + (bufoff) + ldsw + _i * 8192), 16, 0, 0); } while (0)
; #define PG8_LDA(dst, b, h) do { _Pragma("unroll") for (int m = 0; m < 4; ++m) _Pragma("unroll") for (int k = 0; k < 2; ++k) dst[m][k] = *(const PG8_LAS bf16x8*)(lds + PG8_SA(b, h) + aoff + m * 2048 + k * 1024); } while (0)
; #define PG8_LDB(dst, b, h) do { _Pragma("unroll") for (int n = 0; n < 2; ++n) _Pragma("unroll") for (int k = 0; k < 2; ++k) dst[n][k] = *(const PG8_LAS bf16x8*)(lds + PG8_SB(b, h) + boff + n * 2048 + k * 1024); } while (0)
; #define PG8_MMA(ai, bj, At, Bt) do { __builtin_amdgcn_s_setprio(1); _Pragma("unroll") for (int m = 0; m < 4; ++m) _Pragma("unroll") for (int n = 0; n < 2; ++n) _Pragma("unroll") for (int k = 0; k < 2; ++k) \
;         acc[ai][bj][m][n] = __builtin_amdgcn_mfma_f32_16x16x32_bf16(Bt[n][k], At[m][k], acc[ai][bj][m][n], 0, 0, 0); __builtin_amdgcn_s_setprio(0); } while (0)
; #define PG8_BAR __builtin_amdgcn_s_barrier()
; template <class Epi, class Sched, bool ALIGN_EPI = false, bool SP2 = false>
; __device__ __forceinline__ void gemm_phase(PG8_LAS unsigned char* lds, const Gemm g, const Sched& S, const Epi& E, const int wid) {
;     ...
;             PG8_LDB(B0, 0, 0); PG8_LDB(B1, 0, 1); PG8_SCHED; PG8_LDA(At, 0, 0); PG8_STAGE(PG8_SA(1, 1), a1 + hstepA, voffA);
;             PG8_WAIT_V(8); PG8_WAIT_L(0); PG8_BAR; PG8_MMA(0, 0, At, B0); PG8_MMA(0, 1, At, B1); PG8_BAR; PG8_SCHED;
;             PG8_LDA(At, 0, 1); PG8_STAGE(PG8_SB(0, 0), b2, voffB); PG8_STAGE(PG8_SB(0, 1), b2 + hstepB, voffB); PG8_STAGE(PG8_SA(0, 0), a2, voffA);
;             PG8_WAIT_V(8); PG8_WAIT_L(0); PG8_BAR; PG8_MMA(1, 0, At, B0); PG8_MMA(1, 1, At, B1); PG8_BAR; PG8_SCHED;
;             PG8_LDB(B0, 1, 0); PG8_LDB(B1, 1, 1); PG8_SCHED; PG8_LDA(At, 1, 0); PG8_STAGE(PG8_SA(0, 1), a2 + hstepA, voffA);
;             PG8_WAIT_V(8); PG8_WAIT_L(0); PG8_BAR; PG8_MMA(0, 0, At, B0); PG8_MMA(0, 1, At, B1); PG8_BAR; PG8_SCHED;
;             PG8_LDA(At, 1, 1); PG8_STAGE(PG8_SB(1, 0), b3, voffB); PG8_STAGE(PG8_SB(1, 1), b3 + hstepB, voffB); PG8_STAGE(PG8_SA(1, 0), a3, voffA);
;             PG8_WAIT_V(8); PG8_WAIT_L(0); PG8_BAR; PG8_MMA(1, 0, At, B0); PG8_MMA(1, 1, At, B1); PG8_BAR; PG8_SCHED;
	v_mfma_f32_16x16x32_bf16 v[64:67], v[60:63], v[190:193], 0
	v_mfma_f32_16x16x32_bf16 v[52:55], v[72:75], v[190:193], 0
	v_mfma_f32_16x16x32_bf16 v[44:47], v[60:63], v[198:201], 0
	v_mfma_f32_16x16x32_bf16 v[36:39], v[72:75], v[198:201], 0
	v_mfma_f32_16x16x32_bf16 v[28:31], v[60:63], v[206:209], 0
	v_mfma_f32_16x16x32_bf16 v[20:23], v[72:75], v[206:209], 0
	v_mfma_f32_16x16x32_bf16 v[12:15], v[60:63], v[214:217], 0
	v_mfma_f32_16x16x32_bf16 v[4:7], v[72:75], v[214:217], 0
	v_mfma_f32_16x16x32_bf16 v[64:67], v[68:71], v[194:197], v[64:67]
	v_mfma_f32_16x16x32_bf16 v[52:55], v[76:79], v[194:197], v[52:55]
	v_mfma_f32_16x16x32_bf16 v[44:47], v[68:71], v[202:205], v[44:47]
	v_mfma_f32_16x16x32_bf16 v[36:39], v[76:79], v[202:205], v[36:39]
	v_mfma_f32_16x16x32_bf16 v[28:31], v[68:71], v[210:213], v[28:31]
	v_mfma_f32_16x16x32_bf16 v[20:23], v[76:79], v[210:213], v[20:23]
	v_mfma_f32_16x16x32_bf16 v[12:15], v[68:71], v[218:221], v[12:15]
	v_mfma_f32_16x16x32_bf16 v[4:7], v[76:79], v[218:221], v[4:7]
	s_setprio 0
	s_setprio 1
	v_mfma_f32_16x16x32_bf16 v[56:59], v[80:83], v[190:193], 0
	v_mfma_f32_16x16x32_bf16 v[48:51], v[172:175], v[190:193], 0
	v_mfma_f32_16x16x32_bf16 v[40:43], v[80:83], v[198:201], 0
	v_mfma_f32_16x16x32_bf16 v[32:35], v[172:175], v[198:201], 0
	v_mfma_f32_16x16x32_bf16 v[24:27], v[80:83], v[206:209], 0
	v_mfma_f32_16x16x32_bf16 v[16:19], v[172:175], v[206:209], 0
	v_mfma_f32_16x16x32_bf16 v[8:11], v[80:83], v[214:217], 0
	v_mfma_f32_16x16x32_bf16 v[0:3], v[172:175], v[214:217], 0
	v_mfma_f32_16x16x32_bf16 v[56:59], v[84:87], v[194:197], v[56:59]
	v_mfma_f32_16x16x32_bf16 v[48:51], v[186:189], v[194:197], v[48:51]
	v_mfma_f32_16x16x32_bf16 v[40:43], v[84:87], v[202:205], v[40:43]
	v_mfma_f32_16x16x32_bf16 v[32:35], v[186:189], v[202:205], v[32:35]
	v_mfma_f32_16x16x32_bf16 v[24:27], v[84:87], v[210:213], v[24:27]
	v_mfma_f32_16x16x32_bf16 v[16:19], v[186:189], v[210:213], v[16:19]
	v_mfma_f32_16x16x32_bf16 v[8:11], v[84:87], v[218:221], v[8:11]
	v_mfma_f32_16x16x32_bf16 v[0:3], v[186:189], v[218:221], v[0:3]
	s_barrier
	s_setprio 0
	s_add_i32 s69, 0, 0x18000
	s_add_i32 s70, 0, 0x1c000
	v_add_u32_e32 v76, s69, v179
	v_add_u32_e32 v160, s70, v179
	ds_read_b128 v[60:63], v76
	ds_read_b128 v[68:71], v76 offset:1024
	ds_read_b128 v[72:75], v76 offset:2048
	ds_read_b128 v[76:79], v76 offset:3072
	ds_read_b128 v[80:83], v160
	ds_read_b128 v[84:87], v160 offset:1024
	ds_read_b128 v[172:175], v160 offset:2048
	ds_read_b128 v[186:189], v160 offset:3072
	s_add_u32 s48, s48, 0x40000
	s_addc_u32 s49, s49, 0
	s_mov_b32 m0, s58
	v_lshl_add_u64 v[228:229], s[48:49], 0, v[152:153]
	ds_read_b128 v[190:193], v184 offset:32768
	ds_read_b128 v[194:197], v184 offset:33792
	ds_read_b128 v[198:201], v184 offset:34816
	ds_read_b128 v[202:205], v184 offset:35840
	ds_read_b128 v[206:209], v184 offset:36864
	ds_read_b128 v[210:213], v184 offset:37888
	ds_read_b128 v[214:217], v184 offset:38912
	ds_read_b128 v[218:221], v184 offset:39936
	global_load_lds_dwordx4 v[228:229], off
	v_lshl_add_u64 v[228:229], s[48:49], 0, v[156:157]
	s_mov_b32 m0, s59
	s_nop 0
	global_load_lds_dwordx4 v[228:229], off
	s_waitcnt vmcnt(8)
	s_waitcnt lgkmcnt(0)
	s_setprio 1
	s_barrier
	v_mfma_f32_16x16x32_bf16 v[148:151], v[60:63], v[190:193], v[148:151]
	v_mfma_f32_16x16x32_bf16 v[140:143], v[72:75], v[190:193], v[140:143]
	v_mfma_f32_16x16x32_bf16 v[132:135], v[60:63], v[198:201], v[132:135]
	v_mfma_f32_16x16x32_bf16 v[124:127], v[72:75], v[198:201], v[124:127]
	v_mfma_f32_16x16x32_bf16 v[116:119], v[60:63], v[206:209], v[116:119]
	v_mfma_f32_16x16x32_bf16 v[108:111], v[72:75], v[206:209], v[108:111]
	v_mfma_f32_16x16x32_bf16 v[100:103], v[60:63], v[214:217], v[100:103]
	v_mfma_f32_16x16x32_bf16 v[92:95], v[72:75], v[214:217], v[92:95]
	v_mfma_f32_16x16x32_bf16 v[148:151], v[68:71], v[194:197], v[148:151]
	v_mfma_f32_16x16x32_bf16 v[140:143], v[76:79], v[194:197], v[140:143]
	v_mfma_f32_16x16x32_bf16 v[132:135], v[68:71], v[202:205], v[132:135]
	v_mfma_f32_16x16x32_bf16 v[124:127], v[76:79], v[202:205], v[124:127]
	v_mfma_f32_16x16x32_bf16 v[116:119], v[68:71], v[210:213], v[116:119]
	v_mfma_f32_16x16x32_bf16 v[108:111], v[76:79], v[210:213], v[108:111]
	v_mfma_f32_16x16x32_bf16 v[100:103], v[68:71], v[218:221], v[100:103]
	v_mfma_f32_16x16x32_bf16 v[92:95], v[76:79], v[218:221], v[92:95]
	s_setprio 0
	s_setprio 1
	v_mfma_f32_16x16x32_bf16 v[144:147], v[80:83], v[190:193], v[144:147]
	v_mfma_f32_16x16x32_bf16 v[136:139], v[172:175], v[190:193], v[136:139]
	v_mfma_f32_16x16x32_bf16 v[128:131], v[80:83], v[198:201], v[128:131]
	v_mfma_f32_16x16x32_bf16 v[120:123], v[172:175], v[198:201], v[120:123]
	v_mfma_f32_16x16x32_bf16 v[112:115], v[80:83], v[206:209], v[112:115]
	v_mfma_f32_16x16x32_bf16 v[104:107], v[172:175], v[206:209], v[104:107]
	v_mfma_f32_16x16x32_bf16 v[96:99], v[80:83], v[214:217], v[96:99]
	v_mfma_f32_16x16x32_bf16 v[88:91], v[172:175], v[214:217], v[88:91]
	v_mfma_f32_16x16x32_bf16 v[144:147], v[84:87], v[194:197], v[144:147]
	v_mfma_f32_16x16x32_bf16 v[136:139], v[186:189], v[194:197], v[136:139]
	v_mfma_f32_16x16x32_bf16 v[128:131], v[84:87], v[202:205], v[128:131]
	v_mfma_f32_16x16x32_bf16 v[120:123], v[186:189], v[202:205], v[120:123]
	v_mfma_f32_16x16x32_bf16 v[112:115], v[84:87], v[210:213], v[112:115]
	v_mfma_f32_16x16x32_bf16 v[104:107], v[186:189], v[210:213], v[104:107]
	v_mfma_f32_16x16x32_bf16 v[96:99], v[84:87], v[218:221], v[96:99]
	v_mfma_f32_16x16x32_bf16 v[88:91], v[186:189], v[218:221], v[88:91]
	s_barrier
; #define PG8_STAGE(bufoff, gbase, voff) do { _Pragma("unroll") for (int _i = 0; _i < 2; ++_i) \
;         __builtin_amdgcn_global_load_lds((const unsigned*)((const char*)(gbase) + (voff)[_i]), (PG8_LAS unsigned*)(lds + (bufoff) + ldsw + _i * 8192), 16, 0, 0); } while (0)
; #define PG8_LDA(dst, b, h) do { _Pragma("unroll") for (int m = 0; m < 4; ++m) _Pragma("unroll") for (int k = 0; k < 2; ++k) dst[m][k] = *(const PG8_LAS bf16x8*)(lds + PG8_SA(b, h) + aoff + m * 2048 + k * 1024); } while (0)
; #define PG8_LDB(dst, b, h) do { _Pragma("unroll") for (int n = 0; n < 2; ++n) _Pragma("unroll") for (int k = 0; k < 2; ++k) dst[n][k] = *(const PG8_LAS bf16x8*)(lds + PG8_SB(b, h) + boff + n * 2048 + k * 1024); } while (0)
; #define PG8_MMA(ai, bj, At, Bt) do { __builtin_amdgcn_s_setprio(1); _Pragma("unroll") for (int m = 0; m < 4; ++m) _Pragma("unroll") for (int n = 0; n < 2; ++n) _Pragma("unroll") for (int k = 0; k < 2; ++k) \
;         acc[ai][bj][m][n] = __builtin_amdgcn_mfma_f32_16x16x32_bf16(Bt[n][k], At[m][k], acc[ai][bj][m][n], 0, 0, 0); __builtin_amdgcn_s_setprio(0); } while (0)
; #define PG8_WAIT_V(n) asm volatile("s_waitcnt vmcnt(" #n ")" ::: "memory")
; #define PG8_BAR __builtin_amdgcn_s_barrier()
; template <class Epi, class Sched, bool ALIGN_EPI = false, bool SP2 = false>
; __device__ __forceinline__ void gemm_phase(PG8_LAS unsigned char* lds, const Gemm g, const Sched& S, const Epi& E, const int wid) {
;     ...
;         for (int t = 0; t < nt; t += 2) {
;             const bool last = (t == nt - 2);
;             const char* a1 = cA + (size_t)(t + 1) * kstep;
;             const char* a2 = last ? nA : cA + (size_t)(t + 2) * kstep; const char* b2 = last ? nB : cB + (size_t)(t + 2) * kstep;
;             const char* a3 = a2 + kstep; const char* b3 = b2 + kstep;
;             if (last && has_next) S.a_ready(nxt);
;             if constexpr (SP2) {
;             PG8_LDB(B0, 0, 0); PG8_LDB(B1, 0, 1); PG8_SCHED; PG8_LDA(At, 0, 0); PG8_STAGE(PG8_SA(1, 1), a1 + hstepA, voffA);
;             PG8_WAIT_V(8); PG8_WAIT_L(0); PG8_BAR; PG8_MMA(0, 0, At, B0); PG8_MMA(0, 1, At, B1); PG8_BAR; PG8_SCHED;
;     ...
;             PG8_LDA(At, 1, 1); PG8_STAGE(PG8_SB(1, 0), b3, voffB); PG8_STAGE(PG8_SB(1, 1), b3 + hstepB, voffB); PG8_STAGE(PG8_SA(1, 0), a3, voffA);
;             PG8_WAIT_V(8); PG8_WAIT_L(0); PG8_BAR; PG8_MMA(1, 0, At, B0); PG8_MMA(1, 1, At, B1); PG8_BAR; PG8_SCHED;
	s_setprio 0
	s_add_i32 s48, s69, s0
	v_lshl_add_u64 v[176:177], v[176:177], 0, s[22:23]
	s_mov_b32 m0, s48
	ds_read_b128 v[190:193], v184 offset:49152
	ds_read_b128 v[194:197], v184 offset:50176
	ds_read_b128 v[198:201], v184 offset:51200
	ds_read_b128 v[202:205], v184 offset:52224
	ds_read_b128 v[206:209], v184 offset:53248
	ds_read_b128 v[210:213], v184 offset:54272
	ds_read_b128 v[214:217], v184 offset:55296
	ds_read_b128 v[218:221], v184 offset:56320
	global_load_lds_dwordx4 v[176:177], off
	s_add_i32 m0, s48, 0x2000
	s_add_u32 s46, s46, 0x10080
	v_lshl_add_u64 v[176:177], v[222:223], 0, s[22:23]
	s_addc_u32 s47, s47, 0
	s_add_i32 s48, s70, s0
	global_load_lds_dwordx4 v[176:177], off
	v_lshl_add_u64 v[176:177], s[46:47], 0, v[154:155]
	s_mov_b32 m0, s48
	s_nop 0
	global_load_lds_dwordx4 v[176:177], off
	v_lshl_add_u64 v[176:177], s[46:47], 0, v[158:159]
	s_add_i32 m0, s48, 0x2000
	s_nop 0
	global_load_lds_dwordx4 v[176:177], off
	v_lshl_add_u64 v[176:177], v[224:225], 0, s[22:23]
	s_mov_b32 m0, s61
	s_nop 0
	global_load_lds_dwordx4 v[176:177], off
	v_lshl_add_u64 v[176:177], v[226:227], 0, s[22:23]
	s_mov_b32 m0, s62
	s_nop 0
	global_load_lds_dwordx4 v[176:177], off
	s_waitcnt vmcnt(8)
	s_waitcnt lgkmcnt(0)
	s_setprio 1
	s_barrier
	v_mfma_f32_16x16x32_bf16 v[64:67], v[60:63], v[190:193], v[64:67]
	v_mfma_f32_16x16x32_bf16 v[52:55], v[72:75], v[190:193], v[52:55]
	v_mfma_f32_16x16x32_bf16 v[44:47], v[60:63], v[198:201], v[44:47]
	v_mfma_f32_16x16x32_bf16 v[36:39], v[72:75], v[198:201], v[36:39]
	v_mfma_f32_16x16x32_bf16 v[28:31], v[60:63], v[206:209], v[28:31]
	v_mfma_f32_16x16x32_bf16 v[20:23], v[72:75], v[206:209], v[20:23]
	v_mfma_f32_16x16x32_bf16 v[12:15], v[60:63], v[214:217], v[12:15]
	v_mfma_f32_16x16x32_bf16 v[4:7], v[72:75], v[214:217], v[4:7]
	v_mfma_f32_16x16x32_bf16 v[64:67], v[68:71], v[194:197], v[64:67]
	v_mfma_f32_16x16x32_bf16 v[52:55], v[76:79], v[194:197], v[52:55]
	v_mfma_f32_16x16x32_bf16 v[44:47], v[68:71], v[202:205], v[44:47]
	v_mfma_f32_16x16x32_bf16 v[36:39], v[76:79], v[202:205], v[36:39]
	v_mfma_f32_16x16x32_bf16 v[28:31], v[68:71], v[210:213], v[28:31]
	v_mfma_f32_16x16x32_bf16 v[20:23], v[76:79], v[210:213], v[20:23]
	v_mfma_f32_16x16x32_bf16 v[12:15], v[68:71], v[218:221], v[12:15]
	v_mfma_f32_16x16x32_bf16 v[4:7], v[76:79], v[218:221], v[4:7]
	s_setprio 0
	s_setprio 1
	v_mfma_f32_16x16x32_bf16 v[56:59], v[80:83], v[190:193], v[56:59]
	v_mfma_f32_16x16x32_bf16 v[48:51], v[172:175], v[190:193], v[48:51]
	v_mfma_f32_16x16x32_bf16 v[40:43], v[80:83], v[198:201], v[40:43]
	v_mfma_f32_16x16x32_bf16 v[32:35], v[172:175], v[198:201], v[32:35]
	v_mfma_f32_16x16x32_bf16 v[24:27], v[80:83], v[206:209], v[24:27]
	v_mfma_f32_16x16x32_bf16 v[16:19], v[172:175], v[206:209], v[16:19]
	v_mfma_f32_16x16x32_bf16 v[8:11], v[80:83], v[214:217], v[8:11]
	v_mfma_f32_16x16x32_bf16 v[0:3], v[172:175], v[214:217], v[0:3]
	v_mfma_f32_16x16x32_bf16 v[56:59], v[84:87], v[194:197], v[56:59]
	v_mfma_f32_16x16x32_bf16 v[48:51], v[186:189], v[194:197], v[48:51]
	v_mfma_f32_16x16x32_bf16 v[40:43], v[84:87], v[202:205], v[40:43]
	v_mfma_f32_16x16x32_bf16 v[32:35], v[186:189], v[202:205], v[32:35]
	v_mfma_f32_16x16x32_bf16 v[24:27], v[84:87], v[210:213], v[24:27]
	v_mfma_f32_16x16x32_bf16 v[16:19], v[186:189], v[210:213], v[16:19]
	v_mfma_f32_16x16x32_bf16 v[8:11], v[84:87], v[218:221], v[8:11]
	v_mfma_f32_16x16x32_bf16 v[0:3], v[186:189], v[218:221], v[0:3]
	s_barrier
	s_setprio 0
	s_add_u32 s44, s44, 0x100
	s_addc_u32 s45, s45, 0
	s_add_u32 s35, s35, 0x100
	s_addc_u32 s37, s37, 0
	s_cmp_ge_i32 s68, s54
	s_mov_b32 s46, s68
	s_cbranch_scc0 .LBB0_270
	s_branch .Lpeel_after_270
.LBB0_270:
	ds_read_b128 v[60:63], v182
	ds_read_b128 v[68:71], v182 offset:1024
	ds_read_b128 v[72:75], v182 offset:2048
	ds_read_b128 v[76:79], v182 offset:3072
	ds_read_b128 v[80:83], v183
	ds_read_b128 v[84:87], v183 offset:1024
	ds_read_b128 v[172:175], v183 offset:2048
	ds_read_b128 v[186:189], v183 offset:3072
	s_add_i32 s68, s46, 2
	s_add_u32 s47, s44, 0xfffc0080
	s_addc_u32 s48, s45, -1
	s_cmp_eq_u32 s63, s46
	s_cselect_b32 s46, s6, s35
	s_cselect_b32 s49, s39, s48
	s_cselect_b32 s48, s38, s47
	s_cselect_b32 s47, s7, s37
	v_lshl_add_u64 v[176:177], s[44:45], 0, v[162:163]
	s_add_i32 m0, s41, 0xc000
	ds_read_b128 v[190:193], v184
	ds_read_b128 v[194:197], v184 offset:1024
	ds_read_b128 v[198:201], v184 offset:2048
	ds_read_b128 v[202:205], v184 offset:3072
	ds_read_b128 v[206:209], v184 offset:4096
	ds_read_b128 v[210:213], v184 offset:5120
	ds_read_b128 v[214:217], v184 offset:6144
	ds_read_b128 v[218:221], v184 offset:7168
	global_load_lds_dwordx4 v[176:177], off
	v_lshl_add_u64 v[176:177], s[44:45], 0, v[164:165]
	s_add_i32 m0, s41, 0xe000
	s_nop 0
	global_load_lds_dwordx4 v[176:177], off
	s_waitcnt vmcnt(8)
	s_waitcnt lgkmcnt(0)
	s_setprio 1
	s_barrier
; #define PG8_STAGE(bufoff, gbase, voff) do { _Pragma("unroll") for (int _i = 0; _i < 2; ++_i) \
;         __builtin_amdgcn_global_load_lds((const unsigned*)((const char*)(gbase) + (voff)[_i]), (PG8_LAS unsigned*)(lds + (bufoff) + ldsw + _i * 8192), 16, 0, 0); } while (0)
; #define PG8_LDA(dst, b, h) do { _Pragma("unroll") for (int m = 0; m < 4; ++m) _Pragma("unroll") for (int k = 0; k < 2; ++k) dst[m][k] = *(const PG8_LAS bf16x8*)(lds + PG8_SA(b, h) + aoff + m * 2048 + k * 1024); } while (0)
; #define PG8_LDB(dst, b, h) do { _Pragma("unroll") for (int n = 0; n < 2; ++n) _Pragma("unroll") for (int k = 0; k < 2; ++k) dst[n][k] = *(const PG8_LAS bf16x8*)(lds + PG8_SB(b, h) + boff + n * 2048 + k * 1024); } while (0)
; #define PG8_MMA(ai, bj, At, Bt) do { __builtin_amdgcn_s_setprio(1); _Pragma("unroll") for (int m = 0; m < 4; ++m) _Pragma("unroll") for (int n = 0; n < 2; ++n) _Pragma("unroll") for (int k = 0; k < 2; ++k) \
;         acc[ai][bj][m][n] = __builtin_amdgcn_mfma_f32_16x16x32_bf16(Bt[n][k], At[m][k], acc[ai][bj][m][n], 0, 0, 0); __builtin_amdgcn_s_setprio(0); } while (0)
; #define PG8_WAIT_V(n) asm volatile("s_waitcnt vmcnt(" #n ")" ::: "memory")
; #define PG8_WAIT_L(n) asm volatile("s_waitcnt lgkmcnt(" #n ")" ::: "memory")
; #define PG8_BAR __builtin_amdgcn_s_barrier()
; #define PG8_SCHED __builtin_amdgcn_sched_barrier(0)
; template <class Epi, class Sched, bool ALIGN_EPI = false, bool SP2 = false>
; __device__ __forceinline__ void gemm_phase(PG8_LAS unsigned char* lds, const Gemm g, const Sched& S, const Epi& E, const int wid) {
;     ...
;             PG8_LDB(B0, 0, 0); PG8_LDB(B1, 0, 1); PG8_SCHED; PG8_LDA(At, 0, 0); PG8_STAGE(PG8_SA(1, 1), a1 + hstepA, voffA);
;             PG8_WAIT_V(8); PG8_WAIT_L(0); PG8_BAR; PG8_MMA(0, 0, At, B0); PG8_MMA(0, 1, At, B1); PG8_BAR; PG8_SCHED;
;             PG8_LDA(At, 0, 1); PG8_STAGE(PG8_SB(0, 0), b2, voffB); PG8_STAGE(PG8_SB(0, 1), b2 + hstepB, voffB); PG8_STAGE(PG8_SA(0, 0), a2, voffA);
;             PG8_WAIT_V(8); PG8_WAIT_L(0); PG8_BAR; PG8_MMA(1, 0, At, B0); PG8_MMA(1, 1, At, B1); PG8_BAR; PG8_SCHED;
;             PG8_LDB(B0, 1, 0); PG8_LDB(B1, 1, 1); PG8_SCHED; PG8_LDA(At, 1, 0); PG8_STAGE(PG8_SA(0, 1), a2 + hstepA, voffA);
;             PG8_WAIT_V(8); PG8_WAIT_L(0); PG8_BAR; PG8_MMA(0, 0, At, B0); PG8_MMA(0, 1, At, B1); PG8_BAR; PG8_SCHED;
	v_mfma_f32_16x16x32_bf16 v[148:151], v[60:63], v[190:193], v[148:151]
	v_mfma_f32_16x16x32_bf16 v[140:143], v[72:75], v[190:193], v[140:143]
	v_mfma_f32_16x16x32_bf16 v[132:135], v[60:63], v[198:201], v[132:135]
	v_mfma_f32_16x16x32_bf16 v[124:127], v[72:75], v[198:201], v[124:127]
	v_mfma_f32_16x16x32_bf16 v[116:119], v[60:63], v[206:209], v[116:119]
	v_mfma_f32_16x16x32_bf16 v[108:111], v[72:75], v[206:209], v[108:111]
	v_mfma_f32_16x16x32_bf16 v[100:103], v[60:63], v[214:217], v[100:103]
	v_mfma_f32_16x16x32_bf16 v[92:95], v[72:75], v[214:217], v[92:95]
	v_mfma_f32_16x16x32_bf16 v[148:151], v[68:71], v[194:197], v[148:151]
	v_mfma_f32_16x16x32_bf16 v[140:143], v[76:79], v[194:197], v[140:143]
	v_mfma_f32_16x16x32_bf16 v[132:135], v[68:71], v[202:205], v[132:135]
	v_mfma_f32_16x16x32_bf16 v[124:127], v[76:79], v[202:205], v[124:127]
	v_mfma_f32_16x16x32_bf16 v[116:119], v[68:71], v[210:213], v[116:119]
	v_mfma_f32_16x16x32_bf16 v[108:111], v[76:79], v[210:213], v[108:111]
	v_mfma_f32_16x16x32_bf16 v[100:103], v[68:71], v[218:221], v[100:103]
	v_mfma_f32_16x16x32_bf16 v[92:95], v[76:79], v[218:221], v[92:95]
	s_setprio 0
	s_setprio 1
	v_mfma_f32_16x16x32_bf16 v[144:147], v[80:83], v[190:193], v[144:147]
	v_mfma_f32_16x16x32_bf16 v[136:139], v[172:175], v[190:193], v[136:139]
	v_mfma_f32_16x16x32_bf16 v[128:131], v[80:83], v[198:201], v[128:131]
	v_mfma_f32_16x16x32_bf16 v[120:123], v[172:175], v[198:201], v[120:123]
	v_mfma_f32_16x16x32_bf16 v[112:115], v[80:83], v[206:209], v[112:115]
	v_mfma_f32_16x16x32_bf16 v[104:107], v[172:175], v[206:209], v[104:107]
	v_mfma_f32_16x16x32_bf16 v[96:99], v[80:83], v[214:217], v[96:99]
	v_mfma_f32_16x16x32_bf16 v[88:91], v[172:175], v[214:217], v[88:91]
	v_mfma_f32_16x16x32_bf16 v[144:147], v[84:87], v[194:197], v[144:147]
	v_mfma_f32_16x16x32_bf16 v[136:139], v[186:189], v[194:197], v[136:139]
	v_mfma_f32_16x16x32_bf16 v[128:131], v[84:87], v[202:205], v[128:131]
	v_mfma_f32_16x16x32_bf16 v[120:123], v[186:189], v[202:205], v[120:123]
	v_mfma_f32_16x16x32_bf16 v[112:115], v[84:87], v[210:213], v[112:115]
	v_mfma_f32_16x16x32_bf16 v[104:107], v[186:189], v[210:213], v[104:107]
	v_mfma_f32_16x16x32_bf16 v[96:99], v[84:87], v[218:221], v[96:99]
	v_mfma_f32_16x16x32_bf16 v[88:91], v[186:189], v[218:221], v[88:91]
	s_barrier
	s_setprio 0
	s_add_i32 s69, s64, s0
	v_lshl_add_u64 v[176:177], s[46:47], 0, v[154:155]
	s_mov_b32 m0, s69
	ds_read_b128 v[190:193], v184 offset:16384
	ds_read_b128 v[194:197], v184 offset:17408
	ds_read_b128 v[198:201], v184 offset:18432
	ds_read_b128 v[202:205], v184 offset:19456
	ds_read_b128 v[206:209], v184 offset:20480
	ds_read_b128 v[210:213], v184 offset:21504
	ds_read_b128 v[214:217], v184 offset:22528
	ds_read_b128 v[218:221], v184 offset:23552
	global_load_lds_dwordx4 v[176:177], off
	s_add_i32 m0, s69, 0x2000
	s_add_u32 s70, s46, 0x10000
	v_lshl_add_u64 v[222:223], s[46:47], 0, v[158:159]
	s_addc_u32 s71, s47, 0
	s_add_i32 s69, s65, s0
	global_load_lds_dwordx4 v[222:223], off
	v_lshl_add_u64 v[224:225], s[70:71], 0, v[154:155]
	s_mov_b32 m0, s69
	v_lshl_add_u64 v[226:227], s[48:49], 0, v[156:157]
	global_load_lds_dwordx4 v[224:225], off
	v_lshl_add_u64 v[224:225], s[70:71], 0, v[158:159]
	s_add_i32 m0, s69, 0x2000
	s_nop 0
	global_load_lds_dwordx4 v[224:225], off
	v_lshl_add_u64 v[224:225], s[48:49], 0, v[152:153]
	s_mov_b32 m0, s41
	s_nop 0
	global_load_lds_dwordx4 v[224:225], off
	s_mov_b32 m0, s57
	s_nop 0
	global_load_lds_dwordx4 v[226:227], off
	s_waitcnt vmcnt(8)
	s_waitcnt lgkmcnt(0)
	s_setprio 1
	s_barrier
	v_mfma_f32_16x16x32_bf16 v[64:67], v[60:63], v[190:193], v[64:67]
	v_mfma_f32_16x16x32_bf16 v[52:55], v[72:75], v[190:193], v[52:55]
	v_mfma_f32_16x16x32_bf16 v[44:47], v[60:63], v[198:201], v[44:47]
	v_mfma_f32_16x16x32_bf16 v[36:39], v[72:75], v[198:201], v[36:39]
	v_mfma_f32_16x16x32_bf16 v[28:31], v[60:63], v[206:209], v[28:31]
	v_mfma_f32_16x16x32_bf16 v[20:23], v[72:75], v[206:209], v[20:23]
	v_mfma_f32_16x16x32_bf16 v[12:15], v[60:63], v[214:217], v[12:15]
	v_mfma_f32_16x16x32_bf16 v[4:7], v[72:75], v[214:217], v[4:7]
	v_mfma_f32_16x16x32_bf16 v[64:67], v[68:71], v[194:197], v[64:67]
	v_mfma_f32_16x16x32_bf16 v[52:55], v[76:79], v[194:197], v[52:55]
	v_mfma_f32_16x16x32_bf16 v[44:47], v[68:71], v[202:205], v[44:47]
	v_mfma_f32_16x16x32_bf16 v[36:39], v[76:79], v[202:205], v[36:39]
	v_mfma_f32_16x16x32_bf16 v[28:31], v[68:71], v[210:213], v[28:31]
	v_mfma_f32_16x16x32_bf16 v[20:23], v[76:79], v[210:213], v[20:23]
	v_mfma_f32_16x16x32_bf16 v[12:15], v[68:71], v[218:221], v[12:15]
	v_mfma_f32_16x16x32_bf16 v[4:7], v[76:79], v[218:221], v[4:7]
	s_setprio 0
	s_setprio 1
	v_mfma_f32_16x16x32_bf16 v[56:59], v[80:83], v[190:193], v[56:59]
	v_mfma_f32_16x16x32_bf16 v[48:51], v[172:175], v[190:193], v[48:51]
	v_mfma_f32_16x16x32_bf16 v[40:43], v[80:83], v[198:201], v[40:43]
	v_mfma_f32_16x16x32_bf16 v[32:35], v[172:175], v[198:201], v[32:35]
	v_mfma_f32_16x16x32_bf16 v[24:27], v[80:83], v[206:209], v[24:27]
	v_mfma_f32_16x16x32_bf16 v[16:19], v[172:175], v[206:209], v[16:19]
	v_mfma_f32_16x16x32_bf16 v[8:11], v[80:83], v[214:217], v[8:11]
	v_mfma_f32_16x16x32_bf16 v[0:3], v[172:175], v[214:217], v[0:3]
	v_mfma_f32_16x16x32_bf16 v[56:59], v[84:87], v[194:197], v[56:59]
	v_mfma_f32_16x16x32_bf16 v[48:51], v[186:189], v[194:197], v[48:51]
	v_mfma_f32_16x16x32_bf16 v[40:43], v[84:87], v[202:205], v[40:43]
	v_mfma_f32_16x16x32_bf16 v[32:35], v[186:189], v[202:205], v[32:35]
	v_mfma_f32_16x16x32_bf16 v[24:27], v[84:87], v[210:213], v[24:27]
	v_mfma_f32_16x16x32_bf16 v[16:19], v[186:189], v[210:213], v[16:19]
	v_mfma_f32_16x16x32_bf16 v[8:11], v[84:87], v[218:221], v[8:11]
	v_mfma_f32_16x16x32_bf16 v[0:3], v[186:189], v[218:221], v[0:3]
	s_barrier
; #define PG8_STAGE(bufoff, gbase, voff) do { _Pragma("unroll") for (int _i = 0; _i < 2; ++_i) \
;         __builtin_amdgcn_global_load_lds((const unsigned*)((const char*)(gbase) + (voff)[_i]), (PG8_LAS unsigned*)(lds + (bufoff) + ldsw + _i * 8192), 16, 0, 0); } while (0)
; #define PG8_LDA(dst, b, h) do { _Pragma("unroll") for (int m = 0; m < 4; ++m) _Pragma("unroll") for (int k = 0; k < 2; ++k) dst[m][k] = *(const PG8_LAS bf16x8*)(lds + PG8_SA(b, h) + aoff + m * 2048 + k * 1024); } while (0)
; #define PG8_LDB(dst, b, h) do { _Pragma("unroll") for (int n = 0; n < 2; ++n) _Pragma("unroll") for (int k = 0; k < 2; ++k) dst[n][k] = *(const PG8_LAS bf16x8*)(lds + PG8_SB(b, h) + boff + n * 2048 + k * 1024); } while (0)
; #define PG8_MMA(ai, bj, At, Bt) do { __builtin_amdgcn_s_setprio(1); _Pragma("unroll") for (int m = 0; m < 4; ++m) _Pragma("unroll") for (int n = 0; n < 2; ++n) _Pragma("unroll") for (int k = 0; k < 2; ++k) \
;         acc[ai][bj][m][n] = __builtin_amdgcn_mfma_f32_16x16x32_bf16(Bt[n][k], At[m][k], acc[ai][bj][m][n], 0, 0, 0); __builtin_amdgcn_s_setprio(0); } while (0)
; #define PG8_WAIT_V(n) asm volatile("s_waitcnt vmcnt(" #n ")" ::: "memory")
; #define PG8_WAIT_L(n) asm volatile("s_waitcnt lgkmcnt(" #n ")" ::: "memory")
; #define PG8_BAR __builtin_amdgcn_s_barrier()
; #define PG8_SCHED __builtin_amdgcn_sched_barrier(0)
; template <class Epi, class Sched, bool ALIGN_EPI = false, bool SP2 = false>
; __device__ __forceinline__ void gemm_phase(PG8_LAS unsigned char* lds, const Gemm g, const Sched& S, const Epi& E, const int wid) {
;     ...
;             PG8_LDB(B0, 1, 0); PG8_LDB(B1, 1, 1); PG8_SCHED; PG8_LDA(At, 1, 0); PG8_STAGE(PG8_SA(0, 1), a2 + hstepA, voffA);
;             PG8_WAIT_V(8); PG8_WAIT_L(0); PG8_BAR; PG8_MMA(0, 0, At, B0); PG8_MMA(0, 1, At, B1); PG8_BAR; PG8_SCHED;
	s_setprio 0
	s_add_i32 s69, 0, 0x18000
	s_add_i32 s70, 0, 0x1c000
	v_add_u32_e32 v76, s69, v179
	v_add_u32_e32 v160, s70, v179
	ds_read_b128 v[60:63], v76
	ds_read_b128 v[68:71], v76 offset:1024
	ds_read_b128 v[72:75], v76 offset:2048
	ds_read_b128 v[76:79], v76 offset:3072
	ds_read_b128 v[80:83], v160
	ds_read_b128 v[84:87], v160 offset:1024
	ds_read_b128 v[172:175], v160 offset:2048
	ds_read_b128 v[186:189], v160 offset:3072
	s_add_u32 s48, s48, 0x40000
	s_addc_u32 s49, s49, 0
	s_mov_b32 m0, s58
	v_lshl_add_u64 v[228:229], s[48:49], 0, v[152:153]
	ds_read_b128 v[190:193], v184 offset:32768
	ds_read_b128 v[194:197], v184 offset:33792
	ds_read_b128 v[198:201], v184 offset:34816
	ds_read_b128 v[202:205], v184 offset:35840
	ds_read_b128 v[206:209], v184 offset:36864
	ds_read_b128 v[210:213], v184 offset:37888
	ds_read_b128 v[214:217], v184 offset:38912
	ds_read_b128 v[218:221], v184 offset:39936
	global_load_lds_dwordx4 v[228:229], off
	v_lshl_add_u64 v[228:229], s[48:49], 0, v[156:157]
	s_mov_b32 m0, s59
	s_nop 0
	global_load_lds_dwordx4 v[228:229], off
	s_waitcnt vmcnt(8)
	s_waitcnt lgkmcnt(0)
	s_setprio 1
	s_barrier
	v_mfma_f32_16x16x32_bf16 v[148:151], v[60:63], v[190:193], v[148:151]
	v_mfma_f32_16x16x32_bf16 v[140:143], v[72:75], v[190:193], v[140:143]
	v_mfma_f32_16x16x32_bf16 v[132:135], v[60:63], v[198:201], v[132:135]
	v_mfma_f32_16x16x32_bf16 v[124:127], v[72:75], v[198:201], v[124:127]
	v_mfma_f32_16x16x32_bf16 v[116:119], v[60:63], v[206:209], v[116:119]
	v_mfma_f32_16x16x32_bf16 v[108:111], v[72:75], v[206:209], v[108:111]
	v_mfma_f32_16x16x32_bf16 v[100:103], v[60:63], v[214:217], v[100:103]
	v_mfma_f32_16x16x32_bf16 v[92:95], v[72:75], v[214:217], v[92:95]
	v_mfma_f32_16x16x32_bf16 v[148:151], v[68:71], v[194:197], v[148:151]
	v_mfma_f32_16x16x32_bf16 v[140:143], v[76:79], v[194:197], v[140:143]
	v_mfma_f32_16x16x32_bf16 v[132:135], v[68:71], v[202:205], v[132:135]
	v_mfma_f32_16x16x32_bf16 v[124:127], v[76:79], v[202:205], v[124:127]
	v_mfma_f32_16x16x32_bf16 v[116:119], v[68:71], v[210:213], v[116:119]
	v_mfma_f32_16x16x32_bf16 v[108:111], v[76:79], v[210:213], v[108:111]
	v_mfma_f32_16x16x32_bf16 v[100:103], v[68:71], v[218:221], v[100:103]
	v_mfma_f32_16x16x32_bf16 v[92:95], v[76:79], v[218:221], v[92:95]
	s_setprio 0
	s_setprio 1
	v_mfma_f32_16x16x32_bf16 v[144:147], v[80:83], v[190:193], v[144:147]
	v_mfma_f32_16x16x32_bf16 v[136:139], v[172:175], v[190:193], v[136:139]
	v_mfma_f32_16x16x32_bf16 v[128:131], v[80:83], v[198:201], v[128:131]
	v_mfma_f32_16x16x32_bf16 v[120:123], v[172:175], v[198:201], v[120:123]
	v_mfma_f32_16x16x32_bf16 v[112:115], v[80:83], v[206:209], v[112:115]
	v_mfma_f32_16x16x32_bf16 v[104:107], v[172:175], v[206:209], v[104:107]
	v_mfma_f32_16x16x32_bf16 v[96:99], v[80:83], v[214:217], v[96:99]
	v_mfma_f32_16x16x32_bf16 v[88:91], v[172:175], v[214:217], v[88:91]
	v_mfma_f32_16x16x32_bf16 v[144:147], v[84:87], v[194:197], v[144:147]
	v_mfma_f32_16x16x32_bf16 v[136:139], v[186:189], v[194:197], v[136:139]
	v_mfma_f32_16x16x32_bf16 v[128:131], v[84:87], v[202:205], v[128:131]
	v_mfma_f32_16x16x32_bf16 v[120:123], v[186:189], v[202:205], v[120:123]
	v_mfma_f32_16x16x32_bf16 v[112:115], v[84:87], v[210:213], v[112:115]
	v_mfma_f32_16x16x32_bf16 v[104:107], v[186:189], v[210:213], v[104:107]
	v_mfma_f32_16x16x32_bf16 v[96:99], v[84:87], v[218:221], v[96:99]
	v_mfma_f32_16x16x32_bf16 v[88:91], v[186:189], v[218:221], v[88:91]
	s_barrier
; #define PG8_STAGE(bufoff, gbase, voff) do { _Pragma("unroll") for (int _i = 0; _i < 2; ++_i) \
;         __builtin_amdgcn_global_load_lds((const unsigned*)((const char*)(gbase) + (voff)[_i]), (PG8_LAS unsigned*)(lds + (bufoff) + ldsw + _i * 8192), 16, 0, 0); } while (0)
; #define PG8_LDA(dst, b, h) do { _Pragma("unroll") for (int m = 0; m < 4; ++m) _Pragma("unroll") for (int k = 0; k < 2; ++k) dst[m][k] = *(const PG8_LAS bf16x8*)(lds + PG8_SA(b, h) + aoff + m * 2048 + k * 1024); } while (0)
; #define PG8_MMA(ai, bj, At, Bt) do { __builtin_amdgcn_s_setprio(1); _Pragma("unroll") for (int m = 0; m < 4; ++m) _Pragma("unroll") for (int n = 0; n < 2; ++n) _Pragma("unroll") for (int k = 0; k < 2; ++k) \
;         acc[ai][bj][m][n] = __builtin_amdgcn_mfma_f32_16x16x32_bf16(Bt[n][k], At[m][k], acc[ai][bj][m][n], 0, 0, 0); __builtin_amdgcn_s_setprio(0); } while (0)
; #define PG8_WAIT_V(n) asm volatile("s_waitcnt vmcnt(" #n ")" ::: "memory")
; #define PG8_WAIT_L(n) asm volatile("s_waitcnt lgkmcnt(" #n ")" ::: "memory")
; #define PG8_BAR __builtin_amdgcn_s_barrier()
; #define PG8_SCHED __builtin_amdgcn_sched_barrier(0)
; template <class Epi, class Sched, bool ALIGN_EPI = false, bool SP2 = false>
; __device__ __forceinline__ void gemm_phase(PG8_LAS unsigned char* lds, const Gemm g, const Sched& S, const Epi& E, const int wid) {
;     ...
;             PG8_LDA(At, 1, 1); PG8_STAGE(PG8_SB(1, 0), b3, voffB); PG8_STAGE(PG8_SB(1, 1), b3 + hstepB, voffB); PG8_STAGE(PG8_SA(1, 0), a3, voffA);
;             PG8_WAIT_V(8); PG8_WAIT_L(0); PG8_BAR; PG8_MMA(1, 0, At, B0); PG8_MMA(1, 1, At, B1); PG8_BAR; PG8_SCHED;
;     ...
;         if constexpr (ALIGN_EPI) { if (wr == 0) PG8_BAR; }
	s_setprio 0
	s_add_i32 s48, s69, s0
	v_lshl_add_u64 v[176:177], v[176:177], 0, s[22:23]
	s_mov_b32 m0, s48
	ds_read_b128 v[190:193], v184 offset:49152
	ds_read_b128 v[194:197], v184 offset:50176
	ds_read_b128 v[198:201], v184 offset:51200
	ds_read_b128 v[202:205], v184 offset:52224
	ds_read_b128 v[206:209], v184 offset:53248
	ds_read_b128 v[210:213], v184 offset:54272
	ds_read_b128 v[214:217], v184 offset:55296
	ds_read_b128 v[218:221], v184 offset:56320
	global_load_lds_dwordx4 v[176:177], off
	s_add_i32 m0, s48, 0x2000
	s_add_u32 s46, s46, 0x10080
	v_lshl_add_u64 v[176:177], v[222:223], 0, s[22:23]
	s_addc_u32 s47, s47, 0
	s_add_i32 s48, s70, s0
	global_load_lds_dwordx4 v[176:177], off
	v_lshl_add_u64 v[176:177], s[46:47], 0, v[154:155]
	s_mov_b32 m0, s48
	s_nop 0
	global_load_lds_dwordx4 v[176:177], off
	v_lshl_add_u64 v[176:177], s[46:47], 0, v[158:159]
	s_add_i32 m0, s48, 0x2000
	s_nop 0
	global_load_lds_dwordx4 v[176:177], off
	v_lshl_add_u64 v[176:177], v[224:225], 0, s[22:23]
	s_mov_b32 m0, s61
	s_nop 0
	global_load_lds_dwordx4 v[176:177], off
	v_lshl_add_u64 v[176:177], v[226:227], 0, s[22:23]
	s_mov_b32 m0, s62
	s_nop 0
	global_load_lds_dwordx4 v[176:177], off
	s_waitcnt vmcnt(8)
	s_waitcnt lgkmcnt(0)
	s_setprio 1
	s_barrier
	v_mfma_f32_16x16x32_bf16 v[64:67], v[60:63], v[190:193], v[64:67]
	v_mfma_f32_16x16x32_bf16 v[52:55], v[72:75], v[190:193], v[52:55]
	v_mfma_f32_16x16x32_bf16 v[44:47], v[60:63], v[198:201], v[44:47]
	v_mfma_f32_16x16x32_bf16 v[36:39], v[72:75], v[198:201], v[36:39]
	v_mfma_f32_16x16x32_bf16 v[28:31], v[60:63], v[206:209], v[28:31]
	v_mfma_f32_16x16x32_bf16 v[20:23], v[72:75], v[206:209], v[20:23]
	v_mfma_f32_16x16x32_bf16 v[12:15], v[60:63], v[214:217], v[12:15]
	v_mfma_f32_16x16x32_bf16 v[4:7], v[72:75], v[214:217], v[4:7]
	v_mfma_f32_16x16x32_bf16 v[64:67], v[68:71], v[194:197], v[64:67]
	v_mfma_f32_16x16x32_bf16 v[52:55], v[76:79], v[194:197], v[52:55]
	v_mfma_f32_16x16x32_bf16 v[44:47], v[68:71], v[202:205], v[44:47]
	v_mfma_f32_16x16x32_bf16 v[36:39], v[76:79], v[202:205], v[36:39]
	v_mfma_f32_16x16x32_bf16 v[28:31], v[68:71], v[210:213], v[28:31]
	v_mfma_f32_16x16x32_bf16 v[20:23], v[76:79], v[210:213], v[20:23]
	v_mfma_f32_16x16x32_bf16 v[12:15], v[68:71], v[218:221], v[12:15]
	v_mfma_f32_16x16x32_bf16 v[4:7], v[76:79], v[218:221], v[4:7]
	s_setprio 0
	s_setprio 1
	v_mfma_f32_16x16x32_bf16 v[56:59], v[80:83], v[190:193], v[56:59]
	v_mfma_f32_16x16x32_bf16 v[48:51], v[172:175], v[190:193], v[48:51]
	v_mfma_f32_16x16x32_bf16 v[40:43], v[80:83], v[198:201], v[40:43]
	v_mfma_f32_16x16x32_bf16 v[32:35], v[172:175], v[198:201], v[32:35]
	v_mfma_f32_16x16x32_bf16 v[24:27], v[80:83], v[206:209], v[24:27]
	v_mfma_f32_16x16x32_bf16 v[16:19], v[172:175], v[206:209], v[16:19]
	v_mfma_f32_16x16x32_bf16 v[8:11], v[80:83], v[214:217], v[8:11]
	v_mfma_f32_16x16x32_bf16 v[0:3], v[172:175], v[214:217], v[0:3]
	v_mfma_f32_16x16x32_bf16 v[56:59], v[84:87], v[194:197], v[56:59]
	v_mfma_f32_16x16x32_bf16 v[48:51], v[186:189], v[194:197], v[48:51]
	v_mfma_f32_16x16x32_bf16 v[40:43], v[84:87], v[202:205], v[40:43]
	v_mfma_f32_16x16x32_bf16 v[32:35], v[186:189], v[202:205], v[32:35]
	v_mfma_f32_16x16x32_bf16 v[24:27], v[84:87], v[210:213], v[24:27]
	v_mfma_f32_16x16x32_bf16 v[16:19], v[186:189], v[210:213], v[16:19]
	v_mfma_f32_16x16x32_bf16 v[8:11], v[84:87], v[218:221], v[8:11]
	v_mfma_f32_16x16x32_bf16 v[0:3], v[186:189], v[218:221], v[0:3]
	s_barrier
	s_setprio 0
	s_add_u32 s44, s44, 0x100
	s_addc_u32 s45, s45, 0
	s_add_u32 s35, s35, 0x100
	s_addc_u32 s37, s37, 0
	s_cmp_ge_i32 s68, s54
	s_mov_b32 s46, s68
	s_cbranch_scc0 .LBB0_270
.Lpeel_after_270:
	s_and_b64 vcc, exec, s[30:31]
	s_cbranch_vccz .LBB0_273
.LBB0_272:
	s_barrier

; #define PG8_STAGE(bufoff, gbase, voff) do { _Pragma("unroll") for (int _i = 0; _i < 2; ++_i) \
;         __builtin_amdgcn_global_load_lds((const unsigned*)((const char*)(gbase) + (voff)[_i]), (PG8_LAS unsigned*)(lds + (bufoff) + ldsw + _i * 8192), 16, 0, 0); } while (0)
; #define PG8_LDA(dst, b, h) do { _Pragma("unroll") for (int m = 0; m < 4; ++m) _Pragma("unroll") for (int k = 0; k < 2; ++k) dst[m][k] = *(const PG8_LAS bf16x8*)(lds + PG8_SA(b, h) + aoff + m * 2048 + k * 1024); } while (0)
; template <class Epi, class Sched, bool ALIGN_EPI = false, bool SP2 = false>
; __device__ __forceinline__ void gemm_phase(PG8_LAS unsigned char* lds, const Gemm g, const Sched& S, const Epi& E, const int wid) {
;     ...
;         const bool has_next = S.next(ui + 1, nxt);
;         const char* nA = !has_next ? cA : nxt.pn >= g.swap_pn ? (const char*)g.A2 + (size_t)(nxt.pn - g.swap_pn) * tstepA : (const char*)g.A + (size_t)nxt.pm * tstepA + (g.bd ? (size_t)(nxt.pn >> 1) * 512 : 0);
;         const char* nB = !has_next ? cB : nxt.pn >= g.swap_pn ? (const char*)g.B2 + (size_t)nxt.pm * tstepB : (const char*)g.Bt + (size_t)nxt.pn * tstepB;
;         for (int t = 0; t < nt; t += 2) {
;             const bool last = (t == nt - 2);
;             const char* a1 = cA + (size_t)(t + 1) * kstep;
;             const char* a2 = last ? nA : cA + (size_t)(t + 2) * kstep; const char* b2 = last ? nB : cB + (size_t)(t + 2) * kstep;
;             const char* a3 = a2 + kstep; const char* b3 = b2 + kstep;
;             if (last && has_next) S.a_ready(nxt);
;             if constexpr (SP2) {
;             PG8_LDB(B0, 0, 0); PG8_LDB(B1, 0, 1); PG8_SCHED; PG8_LDA(At, 0, 0); PG8_STAGE(PG8_SA(1, 1), a1 + hstepA, voffA);
;             PG8_WAIT_V(8); PG8_WAIT_L(0); PG8_BAR; PG8_MMA(0, 0, At, B0); PG8_MMA(0, 1, At, B1); PG8_BAR; PG8_SCHED;
;             PG8_LDA(At, 0, 1); PG8_STAGE(PG8_SB(0, 0), b2, voffB); PG8_STAGE(PG8_SB(0, 1), b2 + hstepB, voffB); PG8_STAGE(PG8_SA(0, 0), a2, voffA);
;             PG8_WAIT_V(8); PG8_WAIT_L(0); PG8_BAR; PG8_MMA(1, 0, At, B0); PG8_MMA(1, 1, At, B1); PG8_BAR; PG8_SCHED;
;     ...
; #pragma unroll
;         for (int a = 0; a < 2; ++a)
; #pragma unroll
;             for (int b = 0; b < 2; ++b)
; #pragma unroll
;                 for (int m = 0; m < 4; ++m)
; #pragma unroll
;                     for (int n = 0; n < 2; ++n) acc[a][b][m][n] = (f32x4){0.f, 0.f, 0.f, 0.f};
.LBB0_485:
	s_ashr_i32 s51, s50, 31
	s_lshl_b64 s[52:53], s[50:51], 19
	s_add_u32 s11, s94, s52
	s_addc_u32 s51, s95, s53
	s_and_b64 s[52:53], s[44:45], exec
	s_cselect_b32 s53, s51, s57
	s_cselect_b32 s52, s11, s56
	s_ashr_i32 s11, s10, 31
	s_lshl_b64 s[54:55], s[10:11], 19
	s_add_u32 s11, s63, s54
	s_addc_u32 s51, s64, s55
	s_and_b64 s[54:55], s[44:45], exec
	s_cselect_b32 s55, s51, s59
	s_cselect_b32 s54, s11, s58
	s_andn2_b64 vcc, exec, s[4:5]
	s_cbranch_vccnz .LBB0_493
	s_add_u32 s56, s56, 0x40080
	s_addc_u32 s57, s57, 0
	s_add_u32 s11, s58, 0x100
	s_addc_u32 s51, s59, 0
	s_mov_b32 s58, 0
	s_add_i32 s74, s58, 2
	s_add_u32 s59, s56, 0xfffc0080
	s_addc_u32 s60, s57, -1
	s_add_i32 s75, 0, 0x10000
	s_cmp_eq_u32 s72, s58
	s_cselect_b32 s61, s53, s60
	s_cselect_b32 s60, s52, s59
	v_add_u32_e32 v138, s75, v143
	s_cselect_b32 s59, s55, s51
	s_cselect_b32 s58, s54, s11
	s_add_i32 s76, 0, 0x14000
	ds_read_b128 v[170:173], v138
	ds_read_b128 v[174:177], v138 offset:1024
	ds_read_b128 v[178:181], v138 offset:2048
	ds_read_b128 v[182:185], v138 offset:3072
	v_add_u32_e32 v138, s76, v143
	ds_read_b128 v[186:189], v138
	ds_read_b128 v[190:193], v138 offset:1024
	ds_read_b128 v[194:197], v138 offset:2048
	ds_read_b128 v[198:201], v138 offset:3072
	v_lshl_add_u64 v[138:139], s[56:57], 0, v[134:135]
	s_add_i32 m0, s65, 0xc000
	ds_read_b128 v[202:205], v163
	ds_read_b128 v[206:209], v163 offset:1024
	ds_read_b128 v[210:213], v163 offset:2048
	ds_read_b128 v[214:217], v163 offset:3072
	ds_read_b128 v[218:221], v163 offset:4096
	ds_read_b128 v[222:225], v163 offset:5120
	ds_read_b128 v[226:229], v163 offset:6144
	ds_read_b128 v[230:233], v163 offset:7168
	global_load_lds_dwordx4 v[138:139], off
	v_lshl_add_u64 v[138:139], s[56:57], 0, v[136:137]
	s_add_i32 m0, s65, 0xe000
	s_nop 0
	global_load_lds_dwordx4 v[138:139], off
	s_waitcnt vmcnt(8)
	s_waitcnt lgkmcnt(0)
	s_setprio 1
	s_barrier
	v_mfma_f32_16x16x32_bf16 v[124:127], v[170:173], v[202:205], 0
	v_mfma_f32_16x16x32_bf16 v[116:119], v[178:181], v[202:205], 0
	v_mfma_f32_16x16x32_bf16 v[108:111], v[170:173], v[210:213], 0
	v_mfma_f32_16x16x32_bf16 v[100:103], v[178:181], v[210:213], 0
	v_mfma_f32_16x16x32_bf16 v[92:95], v[170:173], v[218:221], 0
	v_mfma_f32_16x16x32_bf16 v[84:87], v[178:181], v[218:221], 0
	v_mfma_f32_16x16x32_bf16 v[76:79], v[170:173], v[226:229], 0
	v_mfma_f32_16x16x32_bf16 v[68:71], v[178:181], v[226:229], 0
	v_mfma_f32_16x16x32_bf16 v[124:127], v[174:177], v[206:209], v[124:127]
	v_mfma_f32_16x16x32_bf16 v[116:119], v[182:185], v[206:209], v[116:119]
	v_mfma_f32_16x16x32_bf16 v[108:111], v[174:177], v[214:217], v[108:111]
	v_mfma_f32_16x16x32_bf16 v[100:103], v[182:185], v[214:217], v[100:103]
	v_mfma_f32_16x16x32_bf16 v[92:95], v[174:177], v[222:225], v[92:95]
	v_mfma_f32_16x16x32_bf16 v[84:87], v[182:185], v[222:225], v[84:87]
	v_mfma_f32_16x16x32_bf16 v[76:79], v[174:177], v[230:233], v[76:79]
	v_mfma_f32_16x16x32_bf16 v[68:71], v[182:185], v[230:233], v[68:71]
	s_setprio 0
	s_setprio 1
	v_mfma_f32_16x16x32_bf16 v[120:123], v[186:189], v[202:205], 0
	v_mfma_f32_16x16x32_bf16 v[112:115], v[194:197], v[202:205], 0
	v_mfma_f32_16x16x32_bf16 v[104:107], v[186:189], v[210:213], 0
	v_mfma_f32_16x16x32_bf16 v[96:99], v[194:197], v[210:213], 0
	v_mfma_f32_16x16x32_bf16 v[88:91], v[186:189], v[218:221], 0
	v_mfma_f32_16x16x32_bf16 v[80:83], v[194:197], v[218:221], 0
	v_mfma_f32_16x16x32_bf16 v[72:75], v[186:189], v[226:229], 0
	v_mfma_f32_16x16x32_bf16 v[64:67], v[194:197], v[226:229], 0
	v_mfma_f32_16x16x32_bf16 v[120:123], v[190:193], v[206:209], v[120:123]
	v_mfma_f32_16x16x32_bf16 v[112:115], v[198:201], v[206:209], v[112:115]
	v_mfma_f32_16x16x32_bf16 v[104:107], v[190:193], v[214:217], v[104:107]
	v_mfma_f32_16x16x32_bf16 v[96:99], v[198:201], v[214:217], v[96:99]
	v_mfma_f32_16x16x32_bf16 v[88:91], v[190:193], v[222:225], v[88:91]
	v_mfma_f32_16x16x32_bf16 v[80:83], v[198:201], v[222:225], v[80:83]
	v_mfma_f32_16x16x32_bf16 v[72:75], v[190:193], v[230:233], v[72:75]
	v_mfma_f32_16x16x32_bf16 v[64:67], v[198:201], v[230:233], v[64:67]
	s_barrier
	s_setprio 0
	s_add_i32 s75, s75, s0
	v_lshl_add_u64 v[138:139], s[58:59], 0, v[146:147]
	s_mov_b32 m0, s75
	ds_read_b128 v[202:205], v163 offset:16384
	ds_read_b128 v[206:209], v163 offset:17408
	ds_read_b128 v[210:213], v163 offset:18432
	ds_read_b128 v[214:217], v163 offset:19456
	ds_read_b128 v[218:221], v163 offset:20480
	ds_read_b128 v[222:225], v163 offset:21504
	ds_read_b128 v[226:229], v163 offset:22528
	ds_read_b128 v[230:233], v163 offset:23552
	global_load_lds_dwordx4 v[138:139], off
	s_add_i32 m0, s75, 0x2000
	s_add_u32 s82, s58, 0x40000
	v_lshl_add_u64 v[234:235], s[58:59], 0, v[128:129]
	s_addc_u32 s83, s59, 0
	s_add_i32 s75, s76, s0
	global_load_lds_dwordx4 v[234:235], off
	v_lshl_add_u64 v[236:237], s[82:83], 0, v[146:147]
	s_mov_b32 m0, s75
	v_lshl_add_u64 v[238:239], s[60:61], 0, v[130:131]
	global_load_lds_dwordx4 v[236:237], off
	v_lshl_add_u64 v[236:237], s[82:83], 0, v[128:129]
	s_add_i32 m0, s75, 0x2000
	s_nop 0
	global_load_lds_dwordx4 v[236:237], off
	v_lshl_add_u64 v[236:237], s[60:61], 0, v[132:133]
	s_mov_b32 m0, s65
	s_nop 0
	global_load_lds_dwordx4 v[236:237], off
	s_mov_b32 m0, s66
	s_nop 0
	global_load_lds_dwordx4 v[238:239], off
	s_waitcnt vmcnt(8)
	s_waitcnt lgkmcnt(0)
	s_setprio 1
	s_barrier
; #define PG8_STAGE(bufoff, gbase, voff) do { _Pragma("unroll") for (int _i = 0; _i < 2; ++_i) \
;         __builtin_amdgcn_global_load_lds((const unsigned*)((const char*)(gbase) + (voff)[_i]), (PG8_LAS unsigned*)(lds + (bufoff) + ldsw + _i * 8192), 16, 0, 0); } while (0)
; #define PG8_LDA(dst, b, h) do { _Pragma("unroll") for (int m = 0; m < 4; ++m) _Pragma("unroll") for (int k = 0; k < 2; ++k) dst[m][k] = *(const PG8_LAS bf16x8*)(lds + PG8_SA(b, h) + aoff + m * 2048 + k * 1024); } while (0)
; #define PG8_LDB(dst, b, h) do { _Pragma("unroll") for (int n = 0; n < 2; ++n) _Pragma("unroll") for (int k = 0; k < 2; ++k) dst[n][k] = *(const PG8_LAS bf16x8*)(lds + PG8_SB(b, h) + boff + n * 2048 + k * 1024); } while (0)
; #define PG8_MMA(ai, bj, At, Bt) do { __builtin_amdgcn_s_setprio(1); _Pragma("unroll") for (int m = 0; m < 4; ++m) _Pragma("unroll") for (int n = 0; n < 2; ++n) _Pragma("unroll") for (int k = 0; k < 2; ++k) \
;         acc[ai][bj][m][n] = __builtin_amdgcn_mfma_f32_16x16x32_bf16(Bt[n][k], At[m][k], acc[ai][bj][m][n], 0, 0, 0); __builtin_amdgcn_s_setprio(0); } while (0)
; #define PG8_BAR __builtin_amdgcn_s_barrier()
; template <class Epi, class Sched, bool ALIGN_EPI = false, bool SP2 = false>
; __device__ __forceinline__ void gemm_phase(PG8_LAS unsigned char* lds, const Gemm g, const Sched& S, const Epi& E, const int wid) {
;     ...
;             PG8_LDB(B0, 0, 0); PG8_LDB(B1, 0, 1); PG8_SCHED; PG8_LDA(At, 0, 0); PG8_STAGE(PG8_SA(1, 1), a1 + hstepA, voffA);
;             PG8_WAIT_V(8); PG8_WAIT_L(0); PG8_BAR; PG8_MMA(0, 0, At, B0); PG8_MMA(0, 1, At, B1); PG8_BAR; PG8_SCHED;
;             PG8_LDA(At, 0, 1); PG8_STAGE(PG8_SB(0, 0), b2, voffB); PG8_STAGE(PG8_SB(0, 1), b2 + hstepB, voffB); PG8_STAGE(PG8_SA(0, 0), a2, voffA);
;             PG8_WAIT_V(8); PG8_WAIT_L(0); PG8_BAR; PG8_MMA(1, 0, At, B0); PG8_MMA(1, 1, At, B1); PG8_BAR; PG8_SCHED;
;             PG8_LDB(B0, 1, 0); PG8_LDB(B1, 1, 1); PG8_SCHED; PG8_LDA(At, 1, 0); PG8_STAGE(PG8_SA(0, 1), a2 + hstepA, voffA);
;             PG8_WAIT_V(8); PG8_WAIT_L(0); PG8_BAR; PG8_MMA(0, 0, At, B0); PG8_MMA(0, 1, At, B1); PG8_BAR; PG8_SCHED;
;             PG8_LDA(At, 1, 1); PG8_STAGE(PG8_SB(1, 0), b3, voffB); PG8_STAGE(PG8_SB(1, 1), b3 + hstepB, voffB); PG8_STAGE(PG8_SA(1, 0), a3, voffA);
;             PG8_WAIT_V(8); PG8_WAIT_L(0); PG8_BAR; PG8_MMA(1, 0, At, B0); PG8_MMA(1, 1, At, B1); PG8_BAR; PG8_SCHED;
	v_mfma_f32_16x16x32_bf16 v[60:63], v[170:173], v[202:205], 0
	v_mfma_f32_16x16x32_bf16 v[52:55], v[178:181], v[202:205], 0
	v_mfma_f32_16x16x32_bf16 v[44:47], v[170:173], v[210:213], 0
	v_mfma_f32_16x16x32_bf16 v[36:39], v[178:181], v[210:213], 0
	v_mfma_f32_16x16x32_bf16 v[28:31], v[170:173], v[218:221], 0
	v_mfma_f32_16x16x32_bf16 v[20:23], v[178:181], v[218:221], 0
	v_mfma_f32_16x16x32_bf16 v[12:15], v[170:173], v[226:229], 0
	v_mfma_f32_16x16x32_bf16 v[4:7], v[178:181], v[226:229], 0
	v_mfma_f32_16x16x32_bf16 v[60:63], v[174:177], v[206:209], v[60:63]
	v_mfma_f32_16x16x32_bf16 v[52:55], v[182:185], v[206:209], v[52:55]
	v_mfma_f32_16x16x32_bf16 v[44:47], v[174:177], v[214:217], v[44:47]
	v_mfma_f32_16x16x32_bf16 v[36:39], v[182:185], v[214:217], v[36:39]
	v_mfma_f32_16x16x32_bf16 v[28:31], v[174:177], v[222:225], v[28:31]
	v_mfma_f32_16x16x32_bf16 v[20:23], v[182:185], v[222:225], v[20:23]
	v_mfma_f32_16x16x32_bf16 v[12:15], v[174:177], v[230:233], v[12:15]
	v_mfma_f32_16x16x32_bf16 v[4:7], v[182:185], v[230:233], v[4:7]
	s_setprio 0
	s_setprio 1
	v_mfma_f32_16x16x32_bf16 v[56:59], v[186:189], v[202:205], 0
	v_mfma_f32_16x16x32_bf16 v[48:51], v[194:197], v[202:205], 0
	v_mfma_f32_16x16x32_bf16 v[40:43], v[186:189], v[210:213], 0
	v_mfma_f32_16x16x32_bf16 v[32:35], v[194:197], v[210:213], 0
	v_mfma_f32_16x16x32_bf16 v[24:27], v[186:189], v[218:221], 0
	v_mfma_f32_16x16x32_bf16 v[16:19], v[194:197], v[218:221], 0
	v_mfma_f32_16x16x32_bf16 v[8:11], v[186:189], v[226:229], 0
	v_mfma_f32_16x16x32_bf16 v[0:3], v[194:197], v[226:229], 0
	v_mfma_f32_16x16x32_bf16 v[56:59], v[190:193], v[206:209], v[56:59]
	v_mfma_f32_16x16x32_bf16 v[48:51], v[198:201], v[206:209], v[48:51]
	v_mfma_f32_16x16x32_bf16 v[40:43], v[190:193], v[214:217], v[40:43]
	v_mfma_f32_16x16x32_bf16 v[32:35], v[198:201], v[214:217], v[32:35]
	v_mfma_f32_16x16x32_bf16 v[24:27], v[190:193], v[222:225], v[24:27]
	v_mfma_f32_16x16x32_bf16 v[16:19], v[198:201], v[222:225], v[16:19]
	v_mfma_f32_16x16x32_bf16 v[8:11], v[190:193], v[230:233], v[8:11]
	v_mfma_f32_16x16x32_bf16 v[0:3], v[198:201], v[230:233], v[0:3]
	s_barrier
	s_setprio 0
	s_add_i32 s75, 0, 0x18000
	v_add_u32_e32 v140, s75, v143
	s_add_i32 s76, 0, 0x1c000
	ds_read_b128 v[170:173], v140
	ds_read_b128 v[174:177], v140 offset:1024
	ds_read_b128 v[178:181], v140 offset:2048
	ds_read_b128 v[182:185], v140 offset:3072
	v_add_u32_e32 v140, s76, v143
	ds_read_b128 v[186:189], v140
	ds_read_b128 v[190:193], v140 offset:1024
	ds_read_b128 v[194:197], v140 offset:2048
	ds_read_b128 v[198:201], v140 offset:3072
	s_add_u32 s60, s60, 0x40000
	s_addc_u32 s61, s61, 0
	s_mov_b32 m0, s67
	v_lshl_add_u64 v[240:241], s[60:61], 0, v[132:133]
	ds_read_b128 v[202:205], v163 offset:32768
	ds_read_b128 v[206:209], v163 offset:33792
	ds_read_b128 v[210:213], v163 offset:34816
	ds_read_b128 v[214:217], v163 offset:35840
	ds_read_b128 v[218:221], v163 offset:36864
	ds_read_b128 v[222:225], v163 offset:37888
	ds_read_b128 v[226:229], v163 offset:38912
	ds_read_b128 v[230:233], v163 offset:39936
	global_load_lds_dwordx4 v[240:241], off
	v_lshl_add_u64 v[240:241], s[60:61], 0, v[130:131]
	s_mov_b32 m0, s68
	s_nop 0
	global_load_lds_dwordx4 v[240:241], off
	s_waitcnt vmcnt(8)
	s_waitcnt lgkmcnt(0)
	s_setprio 1
	s_barrier
	v_mfma_f32_16x16x32_bf16 v[124:127], v[170:173], v[202:205], v[124:127]
	v_mfma_f32_16x16x32_bf16 v[116:119], v[178:181], v[202:205], v[116:119]
	v_mfma_f32_16x16x32_bf16 v[108:111], v[170:173], v[210:213], v[108:111]
	v_mfma_f32_16x16x32_bf16 v[100:103], v[178:181], v[210:213], v[100:103]
	v_mfma_f32_16x16x32_bf16 v[92:95], v[170:173], v[218:221], v[92:95]
	v_mfma_f32_16x16x32_bf16 v[84:87], v[178:181], v[218:221], v[84:87]
	v_mfma_f32_16x16x32_bf16 v[76:79], v[170:173], v[226:229], v[76:79]
	v_mfma_f32_16x16x32_bf16 v[68:71], v[178:181], v[226:229], v[68:71]
	v_mfma_f32_16x16x32_bf16 v[124:127], v[174:177], v[206:209], v[124:127]
	v_mfma_f32_16x16x32_bf16 v[116:119], v[182:185], v[206:209], v[116:119]
	v_mfma_f32_16x16x32_bf16 v[108:111], v[174:177], v[214:217], v[108:111]
	v_mfma_f32_16x16x32_bf16 v[100:103], v[182:185], v[214:217], v[100:103]
	v_mfma_f32_16x16x32_bf16 v[92:95], v[174:177], v[222:225], v[92:95]
	v_mfma_f32_16x16x32_bf16 v[84:87], v[182:185], v[222:225], v[84:87]
	v_mfma_f32_16x16x32_bf16 v[76:79], v[174:177], v[230:233], v[76:79]
	v_mfma_f32_16x16x32_bf16 v[68:71], v[182:185], v[230:233], v[68:71]
	s_setprio 0
	s_setprio 1
	v_mfma_f32_16x16x32_bf16 v[120:123], v[186:189], v[202:205], v[120:123]
	v_mfma_f32_16x16x32_bf16 v[112:115], v[194:197], v[202:205], v[112:115]
	v_mfma_f32_16x16x32_bf16 v[104:107], v[186:189], v[210:213], v[104:107]
	v_mfma_f32_16x16x32_bf16 v[96:99], v[194:197], v[210:213], v[96:99]
	v_mfma_f32_16x16x32_bf16 v[88:91], v[186:189], v[218:221], v[88:91]
	v_mfma_f32_16x16x32_bf16 v[80:83], v[194:197], v[218:221], v[80:83]
	v_mfma_f32_16x16x32_bf16 v[72:75], v[186:189], v[226:229], v[72:75]
	v_mfma_f32_16x16x32_bf16 v[64:67], v[194:197], v[226:229], v[64:67]
	v_mfma_f32_16x16x32_bf16 v[120:123], v[190:193], v[206:209], v[120:123]
	v_mfma_f32_16x16x32_bf16 v[112:115], v[198:201], v[206:209], v[112:115]
	v_mfma_f32_16x16x32_bf16 v[104:107], v[190:193], v[214:217], v[104:107]
	v_mfma_f32_16x16x32_bf16 v[96:99], v[198:201], v[214:217], v[96:99]
	v_mfma_f32_16x16x32_bf16 v[88:91], v[190:193], v[222:225], v[88:91]
	v_mfma_f32_16x16x32_bf16 v[80:83], v[198:201], v[222:225], v[80:83]
	v_mfma_f32_16x16x32_bf16 v[72:75], v[190:193], v[230:233], v[72:75]
	v_mfma_f32_16x16x32_bf16 v[64:67], v[198:201], v[230:233], v[64:67]
	s_barrier
; #define PG8_STAGE(bufoff, gbase, voff) do { _Pragma("unroll") for (int _i = 0; _i < 2; ++_i) \
;         __builtin_amdgcn_global_load_lds((const unsigned*)((const char*)(gbase) + (voff)[_i]), (PG8_LAS unsigned*)(lds + (bufoff) + ldsw + _i * 8192), 16, 0, 0); } while (0)
; #define PG8_LDA(dst, b, h) do { _Pragma("unroll") for (int m = 0; m < 4; ++m) _Pragma("unroll") for (int k = 0; k < 2; ++k) dst[m][k] = *(const PG8_LAS bf16x8*)(lds + PG8_SA(b, h) + aoff + m * 2048 + k * 1024); } while (0)
; #define PG8_MMA(ai, bj, At, Bt) do { __builtin_amdgcn_s_setprio(1); _Pragma("unroll") for (int m = 0; m < 4; ++m) _Pragma("unroll") for (int n = 0; n < 2; ++n) _Pragma("unroll") for (int k = 0; k < 2; ++k) \
;         acc[ai][bj][m][n] = __builtin_amdgcn_mfma_f32_16x16x32_bf16(Bt[n][k], At[m][k], acc[ai][bj][m][n], 0, 0, 0); __builtin_amdgcn_s_setprio(0); } while (0)
; #define PG8_WAIT_V(n) asm volatile("s_waitcnt vmcnt(" #n ")" ::: "memory")
; #define PG8_WAIT_L(n) asm volatile("s_waitcnt lgkmcnt(" #n ")" ::: "memory")
; #define PG8_BAR __builtin_amdgcn_s_barrier()
; #define PG8_SCHED __builtin_amdgcn_sched_barrier(0)
; template <class Epi, class Sched, bool ALIGN_EPI = false, bool SP2 = false>
; __device__ __forceinline__ void gemm_phase(PG8_LAS unsigned char* lds, const Gemm g, const Sched& S, const Epi& E, const int wid) {
;     ...
;         for (int t = 0; t < nt; t += 2) {
;             const bool last = (t == nt - 2);
;     ...
;             PG8_LDA(At, 1, 1); PG8_STAGE(PG8_SB(1, 0), b3, voffB); PG8_STAGE(PG8_SB(1, 1), b3 + hstepB, voffB); PG8_STAGE(PG8_SA(1, 0), a3, voffA);
;             PG8_WAIT_V(8); PG8_WAIT_L(0); PG8_BAR; PG8_MMA(1, 0, At, B0); PG8_MMA(1, 1, At, B1); PG8_BAR; PG8_SCHED;
	s_setprio 0
	s_add_i32 s60, s75, s0
	v_lshl_add_u64 v[138:139], v[138:139], 0, s[80:81]
	s_mov_b32 m0, s60
	ds_read_b128 v[202:205], v163 offset:49152
	ds_read_b128 v[206:209], v163 offset:50176
	ds_read_b128 v[210:213], v163 offset:51200
	ds_read_b128 v[214:217], v163 offset:52224
	ds_read_b128 v[218:221], v163 offset:53248
	ds_read_b128 v[222:225], v163 offset:54272
	ds_read_b128 v[226:229], v163 offset:55296
	ds_read_b128 v[230:233], v163 offset:56320
	global_load_lds_dwordx4 v[138:139], off
	s_add_i32 m0, s60, 0x2000
	s_add_u32 s58, s58, 0x40080
	v_lshl_add_u64 v[138:139], v[234:235], 0, s[80:81]
	s_addc_u32 s59, s59, 0
	s_add_i32 s60, s76, s0
	global_load_lds_dwordx4 v[138:139], off
	v_lshl_add_u64 v[138:139], s[58:59], 0, v[146:147]
	s_mov_b32 m0, s60
	s_nop 0
	global_load_lds_dwordx4 v[138:139], off
	v_lshl_add_u64 v[138:139], s[58:59], 0, v[128:129]
	s_add_i32 m0, s60, 0x2000
	s_nop 0
	global_load_lds_dwordx4 v[138:139], off
	v_lshl_add_u64 v[138:139], v[236:237], 0, s[80:81]
	s_mov_b32 m0, s69
	s_nop 0
	global_load_lds_dwordx4 v[138:139], off
	v_lshl_add_u64 v[138:139], v[238:239], 0, s[80:81]
	s_mov_b32 m0, s70
	s_nop 0
	global_load_lds_dwordx4 v[138:139], off
	s_waitcnt vmcnt(8)
	s_waitcnt lgkmcnt(0)
	s_setprio 1
	s_barrier
	v_mfma_f32_16x16x32_bf16 v[60:63], v[170:173], v[202:205], v[60:63]
	v_mfma_f32_16x16x32_bf16 v[52:55], v[178:181], v[202:205], v[52:55]
	v_mfma_f32_16x16x32_bf16 v[44:47], v[170:173], v[210:213], v[44:47]
	v_mfma_f32_16x16x32_bf16 v[36:39], v[178:181], v[210:213], v[36:39]
	v_mfma_f32_16x16x32_bf16 v[28:31], v[170:173], v[218:221], v[28:31]
	v_mfma_f32_16x16x32_bf16 v[20:23], v[178:181], v[218:221], v[20:23]
	v_mfma_f32_16x16x32_bf16 v[12:15], v[170:173], v[226:229], v[12:15]
	v_mfma_f32_16x16x32_bf16 v[4:7], v[178:181], v[226:229], v[4:7]
	v_mfma_f32_16x16x32_bf16 v[60:63], v[174:177], v[206:209], v[60:63]
	v_mfma_f32_16x16x32_bf16 v[52:55], v[182:185], v[206:209], v[52:55]
	v_mfma_f32_16x16x32_bf16 v[44:47], v[174:177], v[214:217], v[44:47]
	v_mfma_f32_16x16x32_bf16 v[36:39], v[182:185], v[214:217], v[36:39]
	v_mfma_f32_16x16x32_bf16 v[28:31], v[174:177], v[222:225], v[28:31]
	v_mfma_f32_16x16x32_bf16 v[20:23], v[182:185], v[222:225], v[20:23]
	v_mfma_f32_16x16x32_bf16 v[12:15], v[174:177], v[230:233], v[12:15]
	v_mfma_f32_16x16x32_bf16 v[4:7], v[182:185], v[230:233], v[4:7]
	s_setprio 0
	s_setprio 1
	v_mfma_f32_16x16x32_bf16 v[56:59], v[186:189], v[202:205], v[56:59]
	v_mfma_f32_16x16x32_bf16 v[48:51], v[194:197], v[202:205], v[48:51]
	v_mfma_f32_16x16x32_bf16 v[40:43], v[186:189], v[210:213], v[40:43]
	v_mfma_f32_16x16x32_bf16 v[32:35], v[194:197], v[210:213], v[32:35]
	v_mfma_f32_16x16x32_bf16 v[24:27], v[186:189], v[218:221], v[24:27]
	v_mfma_f32_16x16x32_bf16 v[16:19], v[194:197], v[218:221], v[16:19]
	v_mfma_f32_16x16x32_bf16 v[8:11], v[186:189], v[226:229], v[8:11]
	v_mfma_f32_16x16x32_bf16 v[0:3], v[194:197], v[226:229], v[0:3]
	v_mfma_f32_16x16x32_bf16 v[56:59], v[190:193], v[206:209], v[56:59]
	v_mfma_f32_16x16x32_bf16 v[48:51], v[198:201], v[206:209], v[48:51]
	v_mfma_f32_16x16x32_bf16 v[40:43], v[190:193], v[214:217], v[40:43]
	v_mfma_f32_16x16x32_bf16 v[32:35], v[198:201], v[214:217], v[32:35]
	v_mfma_f32_16x16x32_bf16 v[24:27], v[190:193], v[222:225], v[24:27]
	v_mfma_f32_16x16x32_bf16 v[16:19], v[198:201], v[222:225], v[16:19]
	v_mfma_f32_16x16x32_bf16 v[8:11], v[190:193], v[230:233], v[8:11]
	v_mfma_f32_16x16x32_bf16 v[0:3], v[198:201], v[230:233], v[0:3]
	s_barrier
	s_setprio 0
	s_add_u32 s56, s56, 0x100
	s_addc_u32 s57, s57, 0
	s_add_u32 s11, s11, 0x100
	s_addc_u32 s51, s51, 0
	s_cmp_ge_i32 s74, s62
	s_mov_b32 s58, s74
	s_cbranch_scc0 .LBB0_487
	s_branch .Lpeel_after_487

; #define PG8_BAR __builtin_amdgcn_s_barrier()
; template <class Epi, class Sched, bool ALIGN_EPI = false, bool SP2 = false>
; __device__ __forceinline__ void gemm_phase(PG8_LAS unsigned char* lds, const Gemm g, const Sched& S, const Epi& E, const int wid) {
;     ...
;         if constexpr (ALIGN_EPI) { if (wr == 0) PG8_BAR; }
;         if constexpr (!Epi::AFTER_DRAIN) { E(acc, cur, wr, wc, fr, fq); S.done(cur); }
;         if (!has_next) break;
.Lpeel_after_487:
	s_mov_b32 s74, 0x1e000
	s_mov_b32 s75, 0xc000
	s_mov_b32 s82, 0x24000
	s_mov_b32 s83, 0x26000
	s_mov_b32 s61, 0x2c000
	s_mov_b32 s60, 0x32000
	s_mov_b32 s76, 0x38000
	s_mov_b32 s51, 0x2e000
	s_and_b64 vcc, exec, s[6:7]
	s_cbranch_vccz .LBB0_490

; #define PG8_STAGE(bufoff, gbase, voff) do { _Pragma("unroll") for (int _i = 0; _i < 2; ++_i) \
;         __builtin_amdgcn_global_load_lds((const unsigned*)((const char*)(gbase) + (voff)[_i]), (PG8_LAS unsigned*)(lds + (bufoff) + ldsw + _i * 8192), 16, 0, 0); } while (0)
; #define PG8_LDA(dst, b, h) do { _Pragma("unroll") for (int m = 0; m < 4; ++m) _Pragma("unroll") for (int k = 0; k < 2; ++k) dst[m][k] = *(const PG8_LAS bf16x8*)(lds + PG8_SA(b, h) + aoff + m * 2048 + k * 1024); } while (0)
; #define PG8_LDB(dst, b, h) do { _Pragma("unroll") for (int n = 0; n < 2; ++n) _Pragma("unroll") for (int k = 0; k < 2; ++k) dst[n][k] = *(const PG8_LAS bf16x8*)(lds + PG8_SB(b, h) + boff + n * 2048 + k * 1024); } while (0)
; #define PG8_MMA(ai, bj, At, Bt) do { __builtin_amdgcn_s_setprio(1); _Pragma("unroll") for (int m = 0; m < 4; ++m) _Pragma("unroll") for (int n = 0; n < 2; ++n) _Pragma("unroll") for (int k = 0; k < 2; ++k) \
;         acc[ai][bj][m][n] = __builtin_amdgcn_mfma_f32_16x16x32_bf16(Bt[n][k], At[m][k], acc[ai][bj][m][n], 0, 0, 0); __builtin_amdgcn_s_setprio(0); } while (0)
; #define PG8_WAIT_V(n) asm volatile("s_waitcnt vmcnt(" #n ")" ::: "memory")
; #define PG8_WAIT_L(n) asm volatile("s_waitcnt lgkmcnt(" #n ")" ::: "memory")
; #define PG8_BAR __builtin_amdgcn_s_barrier()
; #define PG8_SCHED __builtin_amdgcn_sched_barrier(0)
; template <class Epi, class Sched, bool ALIGN_EPI = false, bool SP2 = false>
; __device__ __forceinline__ void gemm_phase(PG8_LAS unsigned char* lds, const Gemm g, const Sched& S, const Epi& E, const int wid) {
;     ...
;             if constexpr (SP2) {
;             PG8_LDB(B0, 0, 0); PG8_LDB(B1, 0, 1); PG8_SCHED; PG8_LDA(At, 0, 0); PG8_STAGE(PG8_SA(1, 1), a1 + hstepA, voffA);
;             PG8_WAIT_V(8); PG8_WAIT_L(0); PG8_BAR; PG8_MMA(0, 0, At, B0); PG8_MMA(0, 1, At, B1); PG8_BAR; PG8_SCHED;
;             PG8_LDA(At, 0, 1); PG8_STAGE(PG8_SB(0, 0), b2, voffB); PG8_STAGE(PG8_SB(0, 1), b2 + hstepB, voffB); PG8_STAGE(PG8_SA(0, 0), a2, voffA);
;     ...
; #pragma unroll
;         for (int a = 0; a < 2; ++a)
; #pragma unroll
;             for (int b = 0; b < 2; ++b)
; #pragma unroll
;                 for (int m = 0; m < 4; ++m)
; #pragma unroll
;                     for (int n = 0; n < 2; ++n) acc[a][b][m][n] = (f32x4){0.f, 0.f, 0.f, 0.f};
;         cur = nxt; cA = nA; cB = nB; ++ui;
.LBB0_714:
	s_andn2_b64 vcc, exec, s[4:5]
	s_cbranch_vccnz .LBB0_726
	s_add_u32 s52, s52, 0x40080
	s_addc_u32 s53, s53, 0
	s_add_u32 s8, s54, 0x100
	s_addc_u32 s11, s55, 0
	s_mov_b32 s49, 0
	s_add_i32 s69, s49, 2
	s_add_u32 s9, s52, 0xfffc0080
	s_addc_u32 s54, s53, -1
	s_add_i32 s70, 0, 0x10000
	s_cmp_eq_u32 s66, s49
	s_cselect_b32 s57, s47, s54
	s_cselect_b32 s56, s46, s9
	v_add_u32_e32 v146, s70, v162
	s_cselect_b32 s55, s51, s11
	s_cselect_b32 s54, s50, s8
	s_add_i32 s9, 0, 0x14000
	ds_read_b128 v[128:131], v146
	ds_read_b128 v[178:181], v146 offset:1024
	ds_read_b128 v[182:185], v146 offset:2048
	ds_read_b128 v[186:189], v146 offset:3072
	v_add_u32_e32 v146, s9, v162
	ds_read_b128 v[190:193], v146
	ds_read_b128 v[194:197], v146 offset:1024
	ds_read_b128 v[198:201], v146 offset:2048
	ds_read_b128 v[202:205], v146 offset:3072
	v_lshl_add_u64 v[238:239], s[52:53], 0, v[140:141]
	s_add_i32 m0, s59, 0xc000
	ds_read_b128 v[206:209], v176
	ds_read_b128 v[210:213], v176 offset:1024
	ds_read_b128 v[214:217], v176 offset:2048
	ds_read_b128 v[218:221], v176 offset:3072
	ds_read_b128 v[222:225], v176 offset:4096
	ds_read_b128 v[226:229], v176 offset:5120
	ds_read_b128 v[230:233], v176 offset:6144
	ds_read_b128 v[234:237], v176 offset:7168
	global_load_lds_dwordx4 v[238:239], off
	v_lshl_add_u64 v[238:239], s[52:53], 0, v[142:143]
	s_add_i32 m0, s59, 0xe000
	s_nop 0
	global_load_lds_dwordx4 v[238:239], off
	s_waitcnt vmcnt(8)
	s_waitcnt lgkmcnt(0)
	s_setprio 1
	s_barrier
	v_mfma_f32_16x16x32_bf16 v[124:127], v[128:131], v[206:209], 0
	v_mfma_f32_16x16x32_bf16 v[120:123], v[182:185], v[206:209], 0
	v_mfma_f32_16x16x32_bf16 v[108:111], v[128:131], v[214:217], 0
	v_mfma_f32_16x16x32_bf16 v[104:107], v[182:185], v[214:217], 0
	v_mfma_f32_16x16x32_bf16 v[92:95], v[128:131], v[222:225], 0
	v_mfma_f32_16x16x32_bf16 v[88:91], v[182:185], v[222:225], 0
	v_mfma_f32_16x16x32_bf16 v[76:79], v[128:131], v[230:233], 0
	v_mfma_f32_16x16x32_bf16 v[72:75], v[182:185], v[230:233], 0
	v_mfma_f32_16x16x32_bf16 v[124:127], v[178:181], v[210:213], v[124:127]
	v_mfma_f32_16x16x32_bf16 v[120:123], v[186:189], v[210:213], v[120:123]
	v_mfma_f32_16x16x32_bf16 v[108:111], v[178:181], v[218:221], v[108:111]
	v_mfma_f32_16x16x32_bf16 v[104:107], v[186:189], v[218:221], v[104:107]
	v_mfma_f32_16x16x32_bf16 v[92:95], v[178:181], v[226:229], v[92:95]
	v_mfma_f32_16x16x32_bf16 v[88:91], v[186:189], v[226:229], v[88:91]
	v_mfma_f32_16x16x32_bf16 v[76:79], v[178:181], v[234:237], v[76:79]
	v_mfma_f32_16x16x32_bf16 v[72:75], v[186:189], v[234:237], v[72:75]
	s_setprio 0
	s_setprio 1
	v_mfma_f32_16x16x32_bf16 v[116:119], v[190:193], v[206:209], 0
	v_mfma_f32_16x16x32_bf16 v[112:115], v[198:201], v[206:209], 0
	v_mfma_f32_16x16x32_bf16 v[100:103], v[190:193], v[214:217], 0
	v_mfma_f32_16x16x32_bf16 v[96:99], v[198:201], v[214:217], 0
	v_mfma_f32_16x16x32_bf16 v[84:87], v[190:193], v[222:225], 0
	v_mfma_f32_16x16x32_bf16 v[80:83], v[198:201], v[222:225], 0
	v_mfma_f32_16x16x32_bf16 v[68:71], v[190:193], v[230:233], 0
	v_mfma_f32_16x16x32_bf16 v[64:67], v[198:201], v[230:233], 0
	v_mfma_f32_16x16x32_bf16 v[116:119], v[194:197], v[210:213], v[116:119]
	v_mfma_f32_16x16x32_bf16 v[112:115], v[202:205], v[210:213], v[112:115]
	v_mfma_f32_16x16x32_bf16 v[100:103], v[194:197], v[218:221], v[100:103]
	v_mfma_f32_16x16x32_bf16 v[96:99], v[202:205], v[218:221], v[96:99]
	v_mfma_f32_16x16x32_bf16 v[84:87], v[194:197], v[226:229], v[84:87]
	v_mfma_f32_16x16x32_bf16 v[80:83], v[202:205], v[226:229], v[80:83]
	v_mfma_f32_16x16x32_bf16 v[68:71], v[194:197], v[234:237], v[68:71]
	v_mfma_f32_16x16x32_bf16 v[64:67], v[202:205], v[234:237], v[64:67]
	s_barrier
	s_setprio 0
	s_add_i32 s49, s70, s0
	v_lshl_add_u64 v[238:239], s[54:55], 0, v[136:137]
	s_mov_b32 m0, s49
	ds_read_b128 v[206:209], v176 offset:16384
	ds_read_b128 v[210:213], v176 offset:17408
	ds_read_b128 v[214:217], v176 offset:18432
	ds_read_b128 v[218:221], v176 offset:19456
	ds_read_b128 v[222:225], v176 offset:20480
	ds_read_b128 v[226:229], v176 offset:21504
	ds_read_b128 v[230:233], v176 offset:22528
	ds_read_b128 v[234:237], v176 offset:23552
	global_load_lds_dwordx4 v[238:239], off
	s_add_i32 m0, s49, 0x2000
	s_add_u32 s70, s54, 0x40000
	v_lshl_add_u64 v[240:241], s[54:55], 0, v[132:133]
	s_addc_u32 s71, s55, 0
	s_add_i32 s9, s9, s0
	global_load_lds_dwordx4 v[240:241], off
	v_lshl_add_u64 v[242:243], s[70:71], 0, v[136:137]
	s_mov_b32 m0, s9
	v_lshl_add_u64 v[244:245], s[56:57], 0, v[134:135]
	global_load_lds_dwordx4 v[242:243], off
	v_lshl_add_u64 v[242:243], s[70:71], 0, v[132:133]
	s_add_i32 m0, s9, 0x2000
	s_nop 0
	global_load_lds_dwordx4 v[242:243], off
	v_lshl_add_u64 v[242:243], s[56:57], 0, v[138:139]
	s_mov_b32 m0, s59
	s_nop 0
	global_load_lds_dwordx4 v[242:243], off
	s_mov_b32 m0, s60
	s_nop 0
	global_load_lds_dwordx4 v[244:245], off
	s_waitcnt vmcnt(8)
	s_waitcnt lgkmcnt(0)
	s_setprio 1
	s_barrier
; #define PG8_STAGE(bufoff, gbase, voff) do { _Pragma("unroll") for (int _i = 0; _i < 2; ++_i) \
;         __builtin_amdgcn_global_load_lds((const unsigned*)((const char*)(gbase) + (voff)[_i]), (PG8_LAS unsigned*)(lds + (bufoff) + ldsw + _i * 8192), 16, 0, 0); } while (0)
; #define PG8_LDA(dst, b, h) do { _Pragma("unroll") for (int m = 0; m < 4; ++m) _Pragma("unroll") for (int k = 0; k < 2; ++k) dst[m][k] = *(const PG8_LAS bf16x8*)(lds + PG8_SA(b, h) + aoff + m * 2048 + k * 1024); } while (0)
; #define PG8_LDB(dst, b, h) do { _Pragma("unroll") for (int n = 0; n < 2; ++n) _Pragma("unroll") for (int k = 0; k < 2; ++k) dst[n][k] = *(const PG8_LAS bf16x8*)(lds + PG8_SB(b, h) + boff + n * 2048 + k * 1024); } while (0)
; #define PG8_MMA(ai, bj, At, Bt) do { __builtin_amdgcn_s_setprio(1); _Pragma("unroll") for (int m = 0; m < 4; ++m) _Pragma("unroll") for (int n = 0; n < 2; ++n) _Pragma("unroll") for (int k = 0; k < 2; ++k) \
;         acc[ai][bj][m][n] = __builtin_amdgcn_mfma_f32_16x16x32_bf16(Bt[n][k], At[m][k], acc[ai][bj][m][n], 0, 0, 0); __builtin_amdgcn_s_setprio(0); } while (0)
; #define PG8_WAIT_V(n) asm volatile("s_waitcnt vmcnt(" #n ")" ::: "memory")
; #define PG8_WAIT_L(n) asm volatile("s_waitcnt lgkmcnt(" #n ")" ::: "memory")
; #define PG8_BAR __builtin_amdgcn_s_barrier()
; #define PG8_SCHED __builtin_amdgcn_sched_barrier(0)
; template <class Epi, class Sched, bool ALIGN_EPI = false, bool SP2 = false>
; __device__ __forceinline__ void gemm_phase(PG8_LAS unsigned char* lds, const Gemm g, const Sched& S, const Epi& E, const int wid) {
;     ...
;             PG8_LDA(At, 0, 1); PG8_STAGE(PG8_SB(0, 0), b2, voffB); PG8_STAGE(PG8_SB(0, 1), b2 + hstepB, voffB); PG8_STAGE(PG8_SA(0, 0), a2, voffA);
;             PG8_WAIT_V(8); PG8_WAIT_L(0); PG8_BAR; PG8_MMA(1, 0, At, B0); PG8_MMA(1, 1, At, B1); PG8_BAR; PG8_SCHED;
;             PG8_LDB(B0, 1, 0); PG8_LDB(B1, 1, 1); PG8_SCHED; PG8_LDA(At, 1, 0); PG8_STAGE(PG8_SA(0, 1), a2 + hstepA, voffA);
;             PG8_WAIT_V(8); PG8_WAIT_L(0); PG8_BAR; PG8_MMA(0, 0, At, B0); PG8_MMA(0, 1, At, B1); PG8_BAR; PG8_SCHED;
	v_mfma_f32_16x16x32_bf16 v[60:63], v[128:131], v[206:209], 0
	v_mfma_f32_16x16x32_bf16 v[56:59], v[182:185], v[206:209], 0
	v_mfma_f32_16x16x32_bf16 v[44:47], v[128:131], v[214:217], 0
	v_mfma_f32_16x16x32_bf16 v[40:43], v[182:185], v[214:217], 0
	v_mfma_f32_16x16x32_bf16 v[28:31], v[128:131], v[222:225], 0
	v_mfma_f32_16x16x32_bf16 v[24:27], v[182:185], v[222:225], 0
	v_mfma_f32_16x16x32_bf16 v[12:15], v[128:131], v[230:233], 0
	v_mfma_f32_16x16x32_bf16 v[8:11], v[182:185], v[230:233], 0
	v_mfma_f32_16x16x32_bf16 v[60:63], v[178:181], v[210:213], v[60:63]
	v_mfma_f32_16x16x32_bf16 v[56:59], v[186:189], v[210:213], v[56:59]
	v_mfma_f32_16x16x32_bf16 v[44:47], v[178:181], v[218:221], v[44:47]
	v_mfma_f32_16x16x32_bf16 v[40:43], v[186:189], v[218:221], v[40:43]
	v_mfma_f32_16x16x32_bf16 v[28:31], v[178:181], v[226:229], v[28:31]
	v_mfma_f32_16x16x32_bf16 v[24:27], v[186:189], v[226:229], v[24:27]
	v_mfma_f32_16x16x32_bf16 v[12:15], v[178:181], v[234:237], v[12:15]
	v_mfma_f32_16x16x32_bf16 v[8:11], v[186:189], v[234:237], v[8:11]
	s_setprio 0
	s_setprio 1
	v_mfma_f32_16x16x32_bf16 v[52:55], v[190:193], v[206:209], 0
	v_mfma_f32_16x16x32_bf16 v[48:51], v[198:201], v[206:209], 0
	v_mfma_f32_16x16x32_bf16 v[36:39], v[190:193], v[214:217], 0
	v_mfma_f32_16x16x32_bf16 v[32:35], v[198:201], v[214:217], 0
	v_mfma_f32_16x16x32_bf16 v[20:23], v[190:193], v[222:225], 0
	v_mfma_f32_16x16x32_bf16 v[16:19], v[198:201], v[222:225], 0
	v_mfma_f32_16x16x32_bf16 v[4:7], v[190:193], v[230:233], 0
	v_mfma_f32_16x16x32_bf16 v[0:3], v[198:201], v[230:233], 0
	v_mfma_f32_16x16x32_bf16 v[52:55], v[194:197], v[210:213], v[52:55]
	v_mfma_f32_16x16x32_bf16 v[48:51], v[202:205], v[210:213], v[48:51]
	v_mfma_f32_16x16x32_bf16 v[36:39], v[194:197], v[218:221], v[36:39]
	v_mfma_f32_16x16x32_bf16 v[32:35], v[202:205], v[218:221], v[32:35]
	v_mfma_f32_16x16x32_bf16 v[20:23], v[194:197], v[226:229], v[20:23]
	v_mfma_f32_16x16x32_bf16 v[16:19], v[202:205], v[226:229], v[16:19]
	v_mfma_f32_16x16x32_bf16 v[4:7], v[194:197], v[234:237], v[4:7]
	v_mfma_f32_16x16x32_bf16 v[0:3], v[202:205], v[234:237], v[0:3]
	s_barrier
	s_setprio 0
	s_add_i32 s9, 0, 0x18000
	v_add_u32_e32 v146, s9, v162
	s_add_i32 s49, 0, 0x1c000
	ds_read_b128 v[128:131], v146
	ds_read_b128 v[178:181], v146 offset:1024
	ds_read_b128 v[182:185], v146 offset:2048
	ds_read_b128 v[186:189], v146 offset:3072
	v_add_u32_e32 v146, s49, v162
	ds_read_b128 v[190:193], v146
	ds_read_b128 v[194:197], v146 offset:1024
	ds_read_b128 v[198:201], v146 offset:2048
	ds_read_b128 v[202:205], v146 offset:3072
	s_add_u32 s56, s56, 0x40000
	s_addc_u32 s57, s57, 0
	s_mov_b32 m0, s61
	v_lshl_add_u64 v[246:247], s[56:57], 0, v[138:139]
	ds_read_b128 v[206:209], v176 offset:32768
	ds_read_b128 v[210:213], v176 offset:33792
	ds_read_b128 v[214:217], v176 offset:34816
	ds_read_b128 v[218:221], v176 offset:35840
	ds_read_b128 v[222:225], v176 offset:36864
	ds_read_b128 v[226:229], v176 offset:37888
	ds_read_b128 v[230:233], v176 offset:38912
	ds_read_b128 v[234:237], v176 offset:39936
	global_load_lds_dwordx4 v[246:247], off
	v_lshl_add_u64 v[246:247], s[56:57], 0, v[134:135]
	s_mov_b32 m0, s62
	s_nop 0
	global_load_lds_dwordx4 v[246:247], off
	s_waitcnt vmcnt(8)
	s_waitcnt lgkmcnt(0)
	s_setprio 1
	s_barrier
	v_mfma_f32_16x16x32_bf16 v[124:127], v[128:131], v[206:209], v[124:127]
	v_mfma_f32_16x16x32_bf16 v[120:123], v[182:185], v[206:209], v[120:123]
	v_mfma_f32_16x16x32_bf16 v[108:111], v[128:131], v[214:217], v[108:111]
	v_mfma_f32_16x16x32_bf16 v[104:107], v[182:185], v[214:217], v[104:107]
	v_mfma_f32_16x16x32_bf16 v[92:95], v[128:131], v[222:225], v[92:95]
	v_mfma_f32_16x16x32_bf16 v[88:91], v[182:185], v[222:225], v[88:91]
	v_mfma_f32_16x16x32_bf16 v[76:79], v[128:131], v[230:233], v[76:79]
	v_mfma_f32_16x16x32_bf16 v[72:75], v[182:185], v[230:233], v[72:75]
	v_mfma_f32_16x16x32_bf16 v[124:127], v[178:181], v[210:213], v[124:127]
	v_mfma_f32_16x16x32_bf16 v[120:123], v[186:189], v[210:213], v[120:123]
	v_mfma_f32_16x16x32_bf16 v[108:111], v[178:181], v[218:221], v[108:111]
	v_mfma_f32_16x16x32_bf16 v[104:107], v[186:189], v[218:221], v[104:107]
	v_mfma_f32_16x16x32_bf16 v[92:95], v[178:181], v[226:229], v[92:95]
	v_mfma_f32_16x16x32_bf16 v[88:91], v[186:189], v[226:229], v[88:91]
	v_mfma_f32_16x16x32_bf16 v[76:79], v[178:181], v[234:237], v[76:79]
	v_mfma_f32_16x16x32_bf16 v[72:75], v[186:189], v[234:237], v[72:75]
	s_setprio 0
	s_setprio 1
	v_mfma_f32_16x16x32_bf16 v[116:119], v[190:193], v[206:209], v[116:119]
	v_mfma_f32_16x16x32_bf16 v[112:115], v[198:201], v[206:209], v[112:115]
	v_mfma_f32_16x16x32_bf16 v[100:103], v[190:193], v[214:217], v[100:103]
	v_mfma_f32_16x16x32_bf16 v[96:99], v[198:201], v[214:217], v[96:99]
	v_mfma_f32_16x16x32_bf16 v[84:87], v[190:193], v[222:225], v[84:87]
	v_mfma_f32_16x16x32_bf16 v[80:83], v[198:201], v[222:225], v[80:83]
	v_mfma_f32_16x16x32_bf16 v[68:71], v[190:193], v[230:233], v[68:71]
	v_mfma_f32_16x16x32_bf16 v[64:67], v[198:201], v[230:233], v[64:67]
	v_mfma_f32_16x16x32_bf16 v[116:119], v[194:197], v[210:213], v[116:119]
	v_mfma_f32_16x16x32_bf16 v[112:115], v[202:205], v[210:213], v[112:115]
	v_mfma_f32_16x16x32_bf16 v[100:103], v[194:197], v[218:221], v[100:103]
	v_mfma_f32_16x16x32_bf16 v[96:99], v[202:205], v[218:221], v[96:99]
	v_mfma_f32_16x16x32_bf16 v[84:87], v[194:197], v[226:229], v[84:87]
	v_mfma_f32_16x16x32_bf16 v[80:83], v[202:205], v[226:229], v[80:83]
	v_mfma_f32_16x16x32_bf16 v[68:71], v[194:197], v[234:237], v[68:71]
	v_mfma_f32_16x16x32_bf16 v[64:67], v[202:205], v[234:237], v[64:67]
	s_barrier
; #define PG8_STAGE(bufoff, gbase, voff) do { _Pragma("unroll") for (int _i = 0; _i < 2; ++_i) \
;         __builtin_amdgcn_global_load_lds((const unsigned*)((const char*)(gbase) + (voff)[_i]), (PG8_LAS unsigned*)(lds + (bufoff) + ldsw + _i * 8192), 16, 0, 0); } while (0)
; #define PG8_LDA(dst, b, h) do { _Pragma("unroll") for (int m = 0; m < 4; ++m) _Pragma("unroll") for (int k = 0; k < 2; ++k) dst[m][k] = *(const PG8_LAS bf16x8*)(lds + PG8_SA(b, h) + aoff + m * 2048 + k * 1024); } while (0)
; #define PG8_MMA(ai, bj, At, Bt) do { __builtin_amdgcn_s_setprio(1); _Pragma("unroll") for (int m = 0; m < 4; ++m) _Pragma("unroll") for (int n = 0; n < 2; ++n) _Pragma("unroll") for (int k = 0; k < 2; ++k) \
;         acc[ai][bj][m][n] = __builtin_amdgcn_mfma_f32_16x16x32_bf16(Bt[n][k], At[m][k], acc[ai][bj][m][n], 0, 0, 0); __builtin_amdgcn_s_setprio(0); } while (0)
; #define PG8_WAIT_V(n) asm volatile("s_waitcnt vmcnt(" #n ")" ::: "memory")
; #define PG8_WAIT_L(n) asm volatile("s_waitcnt lgkmcnt(" #n ")" ::: "memory")
; #define PG8_BAR __builtin_amdgcn_s_barrier()
; #define PG8_SCHED __builtin_amdgcn_sched_barrier(0)
; template <class Epi, class Sched, bool ALIGN_EPI = false, bool SP2 = false>
; __device__ __forceinline__ void gemm_phase(PG8_LAS unsigned char* lds, const Gemm g, const Sched& S, const Epi& E, const int wid) {
;     ...
;         for (int t = 0; t < nt; t += 2) {
;             const bool last = (t == nt - 2);
;     ...
;             PG8_LDA(At, 1, 1); PG8_STAGE(PG8_SB(1, 0), b3, voffB); PG8_STAGE(PG8_SB(1, 1), b3 + hstepB, voffB); PG8_STAGE(PG8_SA(1, 0), a3, voffA);
;             PG8_WAIT_V(8); PG8_WAIT_L(0); PG8_BAR; PG8_MMA(1, 0, At, B0); PG8_MMA(1, 1, At, B1); PG8_BAR; PG8_SCHED;
	s_setprio 0
	s_add_i32 s9, s9, s0
	v_lshl_add_u64 v[238:239], v[238:239], 0, s[80:81]
	s_mov_b32 m0, s9
	ds_read_b128 v[206:209], v176 offset:49152
	ds_read_b128 v[210:213], v176 offset:50176
	ds_read_b128 v[214:217], v176 offset:51200
	ds_read_b128 v[218:221], v176 offset:52224
	ds_read_b128 v[222:225], v176 offset:53248
	ds_read_b128 v[226:229], v176 offset:54272
	ds_read_b128 v[230:233], v176 offset:55296
	ds_read_b128 v[234:237], v176 offset:56320
	global_load_lds_dwordx4 v[238:239], off
	s_add_i32 m0, s9, 0x2000
	s_add_u32 s54, s54, 0x40080
	v_lshl_add_u64 v[238:239], v[240:241], 0, s[80:81]
	s_addc_u32 s55, s55, 0
	s_add_i32 s9, s49, s0
	global_load_lds_dwordx4 v[238:239], off
	v_lshl_add_u64 v[238:239], s[54:55], 0, v[136:137]
	s_mov_b32 m0, s9
	s_nop 0
	global_load_lds_dwordx4 v[238:239], off
	v_lshl_add_u64 v[238:239], s[54:55], 0, v[132:133]
	s_add_i32 m0, s9, 0x2000
	s_nop 0
	global_load_lds_dwordx4 v[238:239], off
	v_lshl_add_u64 v[238:239], v[242:243], 0, s[80:81]
	s_mov_b32 m0, s63
	s_nop 0
	global_load_lds_dwordx4 v[238:239], off
	v_lshl_add_u64 v[238:239], v[244:245], 0, s[80:81]
	s_mov_b32 m0, s64
	s_nop 0
	global_load_lds_dwordx4 v[238:239], off
	s_waitcnt vmcnt(8)
	s_waitcnt lgkmcnt(0)
	s_setprio 1
	s_barrier
	v_mfma_f32_16x16x32_bf16 v[60:63], v[128:131], v[206:209], v[60:63]
	v_mfma_f32_16x16x32_bf16 v[56:59], v[182:185], v[206:209], v[56:59]
	v_mfma_f32_16x16x32_bf16 v[44:47], v[128:131], v[214:217], v[44:47]
	v_mfma_f32_16x16x32_bf16 v[40:43], v[182:185], v[214:217], v[40:43]
	v_mfma_f32_16x16x32_bf16 v[28:31], v[128:131], v[222:225], v[28:31]
	v_mfma_f32_16x16x32_bf16 v[24:27], v[182:185], v[222:225], v[24:27]
	v_mfma_f32_16x16x32_bf16 v[12:15], v[128:131], v[230:233], v[12:15]
	v_mfma_f32_16x16x32_bf16 v[8:11], v[182:185], v[230:233], v[8:11]
	v_mfma_f32_16x16x32_bf16 v[60:63], v[178:181], v[210:213], v[60:63]
	v_mfma_f32_16x16x32_bf16 v[56:59], v[186:189], v[210:213], v[56:59]
	v_mfma_f32_16x16x32_bf16 v[44:47], v[178:181], v[218:221], v[44:47]
	v_mfma_f32_16x16x32_bf16 v[40:43], v[186:189], v[218:221], v[40:43]
	v_mfma_f32_16x16x32_bf16 v[28:31], v[178:181], v[226:229], v[28:31]
	v_mfma_f32_16x16x32_bf16 v[24:27], v[186:189], v[226:229], v[24:27]
	v_mfma_f32_16x16x32_bf16 v[12:15], v[178:181], v[234:237], v[12:15]
	v_mfma_f32_16x16x32_bf16 v[8:11], v[186:189], v[234:237], v[8:11]
	s_setprio 0
	s_setprio 1
	v_mfma_f32_16x16x32_bf16 v[52:55], v[190:193], v[206:209], v[52:55]
	v_mfma_f32_16x16x32_bf16 v[48:51], v[198:201], v[206:209], v[48:51]
	v_mfma_f32_16x16x32_bf16 v[36:39], v[190:193], v[214:217], v[36:39]
	v_mfma_f32_16x16x32_bf16 v[32:35], v[198:201], v[214:217], v[32:35]
	v_mfma_f32_16x16x32_bf16 v[20:23], v[190:193], v[222:225], v[20:23]
	v_mfma_f32_16x16x32_bf16 v[16:19], v[198:201], v[222:225], v[16:19]
	v_mfma_f32_16x16x32_bf16 v[4:7], v[190:193], v[230:233], v[4:7]
	v_mfma_f32_16x16x32_bf16 v[0:3], v[198:201], v[230:233], v[0:3]
	v_mfma_f32_16x16x32_bf16 v[52:55], v[194:197], v[210:213], v[52:55]
	v_mfma_f32_16x16x32_bf16 v[48:51], v[202:205], v[210:213], v[48:51]
	v_mfma_f32_16x16x32_bf16 v[36:39], v[194:197], v[218:221], v[36:39]
	v_mfma_f32_16x16x32_bf16 v[32:35], v[202:205], v[218:221], v[32:35]
	v_mfma_f32_16x16x32_bf16 v[20:23], v[194:197], v[226:229], v[20:23]
	v_mfma_f32_16x16x32_bf16 v[16:19], v[202:205], v[226:229], v[16:19]
	v_mfma_f32_16x16x32_bf16 v[4:7], v[194:197], v[234:237], v[4:7]
	v_mfma_f32_16x16x32_bf16 v[0:3], v[202:205], v[234:237], v[0:3]
	s_barrier
	s_setprio 0
	s_add_u32 s52, s52, 0x100
	s_addc_u32 s53, s53, 0
	s_add_u32 s8, s8, 0x100
	s_addc_u32 s11, s11, 0
	s_cmp_ge_i32 s69, s58
	s_mov_b32 s49, s69
	s_cbranch_scc0 .LBB0_716
	s_branch .Lpeel_after_716

; #define PG8_BAR __builtin_amdgcn_s_barrier()
; template <class Epi, class Sched, bool ALIGN_EPI = false, bool SP2 = false>
; __device__ __forceinline__ void gemm_phase(PG8_LAS unsigned char* lds, const Gemm g, const Sched& S, const Epi& E, const int wid) {
;     ...
;         if constexpr (ALIGN_EPI) { if (wr == 0) PG8_BAR; }
;         if constexpr (!Epi::AFTER_DRAIN) { E(acc, cur, wr, wc, fr, fq); S.done(cur); }
;         if (!has_next) break;
.Lpeel_after_716:
	s_mov_b32 s70, 0x1a000
	s_mov_b32 s71, 0xa000
	s_mov_b32 s56, 0x34000
	s_mov_b32 s57, 0x36000
	s_and_b64 vcc, exec, s[6:7]
	s_cbranch_vccz .LBB0_719
